# diff-attn: next tile's K fragments prefetched from LDS right after the loop barrier (cross-iteration), QK phase starts without LDS waits
# speedup vs baseline: 1.1307x; 1.0039x over previous
; template <int DQK, bool BIAS>
; __device__ __forceinline__ void attn_pass(const hf* __restrict__ Q, int ldq, const hf* __restrict__ Kp, int ldk, const hf* __restrict__ VT,
;                                           int s0, int L, int q0, float scale_l2, const float* sBias, f4 (&oacc)[8][4], char* smem) {
;     ...
;   h8 qf[4][NKS];
; #pragma unroll
;   for (int nq = 0; nq < 4; ++nq)
; #pragma unroll
;     for (int ks = 0; ks < NKS; ++ks) qf[nq][ks] = *(const h8*)(Q + (size_t)(s0 + q0 + wv * 64 + nq * 16 + fr) * ldq + ks * 32 + fq * 8);
;   float mrun[4], lrun[4];
; #pragma unroll
;   for (int nq = 0; nq < 4; ++nq) { mrun[nq] = -1e30f; lrun[nq] = 0.f; }
; #pragma unroll
;   for (int md = 0; md < 8; ++md)
; #pragma unroll
;     for (int nq = 0; nq < 4; ++nq) oacc[md][nq] = (f4){0.f, 0.f, 0.f, 0.f};
;   u4 rk[NKL], rv[4];
;   auto loadKV = [&](int kt) {
;     const int key0 = kt * 64;
; #pragma unroll
;     for (int i = 0; i < NKL; ++i) rk[i] = *(const u4*)(Kp + (size_t)(s0 + key0 + (tid >> 2)) * ldk + ((tid & 3) + 4 * i) * 8);
; #pragma unroll
;     for (int i = 0; i < 4; ++i) { int idx = tid + 256 * i, dv = idx >> 3, ch = idx & 7; rv[i] = *(const u4*)(VT + (size_t)dv * T_TOK + s0 + key0 + ch * 8); }
;   };
;   auto storeKV = [&](int st) {
;     hf* sK = sbase + st * A_STG; hf* sVT = sK + 64 * 104;
; #pragma unroll
;     for (int i = 0; i < NKL; ++i) *(u4*)(sK + (tid >> 2) * KS + (((tid & 3) ^ (((tid >> 4) ^ (tid >> 5)) & 1)) + 4 * i) * 8) = rk[i];
; #pragma unroll
;     for (int i = 0; i < 4; ++i) { int idx = tid + 256 * i, dv = idx >> 3, ch = idx & 7; *(u4*)(sVT + dv * 72 + ch * 8) = rv[i]; }
;   };
;   const int nkt = L >> 6;
;   __syncthreads();
;   loadKV(0); storeKV(0);
;   if (nkt > 1) loadKV(1);
;   __syncthreads();
.LBB0_1947:
	s_xor_b64 s[62:63], s[26:27], -1
	s_lshl_b64 s[16:17], s[16:17], 1
	s_add_u32 s26, s74, s16
	s_addc_u32 s27, s75, s17
	v_mov_b32_e32 v58, v224
	s_add_u32 s16, s89, s16
	s_addc_u32 s17, s90, s17
	v_bfe_u32 v60, v58, 4, 2
	v_and_b32_e32 v61, 0xffffffc0, v58
	v_and_b32_e32 v59, 15, v58
	v_add_u32_e32 v0, s91, v61
	v_lshlrev_b32_e32 v196, 4, v60
	v_ashrrev_i32_e32 v62, 2, v58
	v_or_b32_e32 v26, v0, v59
	v_lshl_add_u64 v[24:25], s[26:27], 0, v[196:197]
	v_add_u32_e32 v231, s72, v62
	v_mov_b64_e32 v[56:57], s[16:17]
	v_lshlrev_b32_e32 v42, 3, v58
	v_lshlrev_b32_e32 v34, 4, v58
	v_mad_i64_i32 v[4:5], s[26:27], v26, s35, v[24:25]
	v_or_b32_e32 v8, 16, v26
	v_or_b32_e32 v16, 32, v26
	v_or_b32_e32 v26, 48, v26
	v_mad_i64_i32 v[32:33], s[26:27], v231, s35, v[56:57]
	v_and_b32_e32 v196, 48, v34
	v_ashrrev_i32_e32 v63, 3, v58
	v_mov_b64_e32 v[52:53], s[38:39]
	v_and_b32_e32 v42, 56, v42
	v_mad_i64_i32 v[12:13], s[26:27], v8, s35, v[24:25]
	v_mad_i64_i32 v[20:21], s[26:27], v16, s35, v[24:25]
	v_mad_i64_i32 v[28:29], s[26:27], v26, s35, v[24:25]
	v_lshl_add_u64 v[36:37], v[32:33], 0, v[196:197]
	v_mad_i64_i32 v[40:41], s[26:27], v63, s76, v[52:53]
	v_lshlrev_b32_e32 v210, 1, v42
	v_mov_b32_e32 v211, v197
	global_load_dwordx4 v[0:3], v[4:5], off
	s_nop 0
	global_load_dwordx4 v[4:7], v[4:5], off offset:64
	s_nop 0
	global_load_dwordx4 v[8:11], v[12:13], off
	s_nop 0
	global_load_dwordx4 v[12:15], v[12:13], off offset:64
	s_nop 0
	global_load_dwordx4 v[16:19], v[20:21], off
	s_nop 0
	global_load_dwordx4 v[20:23], v[20:21], off offset:64
	s_nop 0
	global_load_dwordx4 v[24:27], v[28:29], off
	s_nop 0
	global_load_dwordx4 v[28:31], v[28:29], off offset:64
	s_waitcnt lgkmcnt(0)
	s_barrier
	global_load_dwordx4 v[32:35], v[36:37], off
	s_nop 0
	global_load_dwordx4 v[36:39], v[36:37], off offset:64
	v_lshl_add_u64 v[212:213], v[40:41], 0, v[210:211]
	v_add_u32_e32 v44, 0x100, v58
	global_load_dwordx4 v[40:43], v[212:213], off
	v_ashrrev_i32_e32 v64, 3, v44
	v_mad_i64_i32 v[44:45], s[26:27], v64, s76, v[52:53]
	v_lshl_add_u64 v[214:215], v[44:45], 0, v[210:211]
	v_add_u32_e32 v48, 0x200, v58
	global_load_dwordx4 v[44:47], v[214:215], off
	v_ashrrev_i32_e32 v65, 3, v48
	v_mad_i64_i32 v[48:49], s[26:27], v65, s76, v[52:53]
	v_lshl_add_u64 v[216:217], v[48:49], 0, v[210:211]
	v_add_u32_e32 v54, 0x300, v58
	global_load_dwordx4 v[48:51], v[216:217], off
	v_ashrrev_i32_e32 v66, 3, v54
	v_mad_i64_i32 v[52:53], s[26:27], v66, s76, v[52:53]
	v_lshl_add_u64 v[218:219], v[52:53], 0, v[210:211]
	global_load_dwordx4 v[52:55], v[218:219], off
	v_lshrrev_b32_e32 v67, 4, v58
	v_lshrrev_b32_e32 v69, 5, v58
	v_and_b32_e32 v68, 3, v58
	v_xor_b32_e32 v67, v67, v69
	v_mul_lo_u32 v70, v62, s77
	v_mul_lo_u32 v63, v63, s77
	v_bitop3_b32 v67, v67, v68, 1 bitop3:0x6c
	v_lshlrev_b32_e32 v211, 1, v70
	v_lshlrev_b32_e32 v232, 1, v63
	v_lshlrev_b32_e32 v63, 3, v67
	v_lshlrev_b32_e32 v67, 4, v67
	v_add3_u32 v67, 16, v211, v67
	v_lshlrev_b32_e32 v237, 2, v60
	v_lshl_add_u64 v[220:221], s[16:17], 0, v[196:197]
	v_mul_u32_u24_e32 v238, 0x48, v59
	v_mul_u32_u24_e32 v240, 0x90, v59
	s_mov_b32 s16, 0
	v_accvgpr_write_b32 a0, 0
	s_waitcnt vmcnt(5)
	ds_write_b128 v67, v[32:35]
	s_waitcnt vmcnt(4)
	ds_write_b128 v67, v[36:39] offset:64
	v_add3_u32 v32, 16, v232, v210
	global_load_dwordx4 a[192:195], v[212:213], off offset:128
	global_load_dwordx4 a[196:199], v[214:215], off offset:128
	s_waitcnt vmcnt(5)
	ds_write_b128 v32, v[40:43] offset:13312
	v_mul_lo_u32 v32, v64, s77
	v_lshlrev_b32_e32 v234, 1, v32
	v_add3_u32 v32, 16, v234, v210
	global_load_dwordx4 a[208:211], v[216:217], off offset:128
	global_load_dwordx4 a[212:215], v[218:219], off offset:128
	s_waitcnt vmcnt(6)
	ds_write_b128 v32, v[44:47] offset:13312
	v_mul_lo_u32 v32, v65, s77
	v_lshlrev_b32_e32 v235, 1, v32
	v_add3_u32 v32, 16, v235, v210
	v_accvgpr_write_b32 a1, 0
	s_waitcnt vmcnt(5)
	ds_write_b128 v32, v[48:51] offset:13312
	v_mul_lo_u32 v32, v66, s77
	v_lshlrev_b32_e32 v236, 1, v32
	v_add3_u32 v32, 16, v236, v210
	v_accvgpr_write_b32 a2, 0
	s_waitcnt vmcnt(4)
	ds_write_b128 v32, v[52:55] offset:13312
	v_add_u32_e32 v32, s92, v62
	v_mad_i64_i32 v[32:33], s[26:27], v32, s35, v[56:57]
	v_lshl_add_u64 v[32:33], v[32:33], 0, v[196:197]
	global_load_dwordx4 a[200:203], v[32:33], off
	global_load_dwordx4 a[204:207], v[32:33], off offset:64
	v_lshrrev_b32_e32 v32, 2, v58
	v_lshrrev_b32_e32 v33, 3, v58
	v_xor_b32_e32 v32, v32, v33
	v_bitop3_b32 v32, v32, v60, 1 bitop3:0x6c
	v_lshlrev_b32_e32 v239, 4, v32
	v_add_u32_e32 v32, s93, v237
	v_sub_u32_e32 v32, v32, v59
	v_sub_u32_e32 v241, v32, v61
	v_accvgpr_write_b32 a3, 0
	v_accvgpr_write_b32 a4, 0
	v_accvgpr_write_b32 a5, 0
	v_accvgpr_write_b32 a6, 0
	v_accvgpr_write_b32 a7, 0
	v_accvgpr_write_b32 a12, 0
	v_accvgpr_write_b32 a13, 0
	v_accvgpr_write_b32 a14, 0
	v_accvgpr_write_b32 a15, 0
	v_accvgpr_write_b32 a20, 0
	v_accvgpr_write_b32 a21, 0
	v_accvgpr_write_b32 a22, 0
	v_accvgpr_write_b32 a23, 0
	v_accvgpr_write_b32 a8, 0
	v_accvgpr_write_b32 a9, 0
	v_accvgpr_write_b32 a10, 0
	v_accvgpr_write_b32 a11, 0
	v_accvgpr_write_b32 a16, 0
	v_accvgpr_write_b32 a17, 0
	v_accvgpr_write_b32 a18, 0
	v_accvgpr_write_b32 a19, 0
	v_accvgpr_write_b32 a28, 0
	v_accvgpr_write_b32 a29, 0
	v_accvgpr_write_b32 a30, 0
	v_accvgpr_write_b32 a31, 0
	v_accvgpr_write_b32 a32, 0
	v_accvgpr_write_b32 a33, 0
	v_accvgpr_write_b32 a34, 0
	v_accvgpr_write_b32 a35, 0
	v_accvgpr_write_b32 a24, 0
	v_accvgpr_write_b32 a25, 0
	v_accvgpr_write_b32 a26, 0
	v_accvgpr_write_b32 a27, 0
	v_accvgpr_write_b32 a36, 0
	v_accvgpr_write_b32 a37, 0
	v_accvgpr_write_b32 a38, 0
	v_accvgpr_write_b32 a39, 0
	v_accvgpr_write_b32 a40, 0
; template <int DQK, bool BIAS>
; __device__ __forceinline__ void attn_pass(const hf* __restrict__ Q, int ldq, const hf* __restrict__ Kp, int ldk, const hf* __restrict__ VT,
;                                           int s0, int L, int q0, float scale_l2, const float* sBias, f4 (&oacc)[8][4], char* smem) {
;     ...
; #pragma unroll
;   for (int md = 0; md < 8; ++md)
; #pragma unroll
;     for (int nq = 0; nq < 4; ++nq) oacc[md][nq] = (f4){0.f, 0.f, 0.f, 0.f};
;   u4 rk[NKL], rv[4];
;   auto loadKV = [&](int kt) {
;     const int key0 = kt * 64;
; #pragma unroll
;     for (int i = 0; i < NKL; ++i) rk[i] = *(const u4*)(Kp + (size_t)(s0 + key0 + (tid >> 2)) * ldk + ((tid & 3) + 4 * i) * 8);
; #pragma unroll
;     for (int i = 0; i < 4; ++i) { int idx = tid + 256 * i, dv = idx >> 3, ch = idx & 7; rv[i] = *(const u4*)(VT + (size_t)dv * T_TOK + s0 + key0 + ch * 8); }
;   };
;   auto storeKV = [&](int st) {
;     hf* sK = sbase + st * A_STG; hf* sVT = sK + 64 * 104;
; #pragma unroll
;     for (int i = 0; i < NKL; ++i) *(u4*)(sK + (tid >> 2) * KS + (((tid & 3) ^ (((tid >> 4) ^ (tid >> 5)) & 1)) + 4 * i) * 8) = rk[i];
; #pragma unroll
;     for (int i = 0; i < 4; ++i) { int idx = tid + 256 * i, dv = idx >> 3, ch = idx & 7; *(u4*)(sVT + dv * 72 + ch * 8) = rv[i]; }
;   };
;   const int nkt = L >> 6;
;   __syncthreads();
;   loadKV(0); storeKV(0);
;   if (nkt > 1) loadKV(1);
;   __syncthreads();
;   for (int kt = 0; kt < nkt; ++kt) {
;     const hf* sK = sbase + (kt & 1) * A_STG; const hf* sVT = sK + 64 * 104;
;     f4 sacc[4][4];
; #pragma unroll
;     for (int mk = 0; mk < 4; ++mk) {
;       h8 kf[NKS];
; #pragma unroll
;       for (int ks = 0; ks < NKS; ++ks) kf[ks] = *(const h8*)(sK + (mk * 16 + fr) * KS + ks * 32 + (fq ^ (((fr >> 2) ^ (fr >> 3)) & 1)) * 8);
	v_accvgpr_write_b32 a41, 0
	v_accvgpr_write_b32 a42, 0
	v_accvgpr_write_b32 a43, 0
	v_accvgpr_write_b32 a48, 0
	v_accvgpr_write_b32 a49, 0
	v_accvgpr_write_b32 a50, 0
	v_accvgpr_write_b32 a51, 0
	v_accvgpr_write_b32 a44, 0
	v_accvgpr_write_b32 a45, 0
	v_accvgpr_write_b32 a46, 0
	v_accvgpr_write_b32 a47, 0
	v_accvgpr_write_b32 a52, 0
	v_accvgpr_write_b32 a53, 0
	v_accvgpr_write_b32 a54, 0
	v_accvgpr_write_b32 a55, 0
	v_accvgpr_write_b32 a56, 0
	v_accvgpr_write_b32 a57, 0
	v_accvgpr_write_b32 a58, 0
	v_accvgpr_write_b32 a59, 0
	v_accvgpr_write_b32 a60, 0
	v_accvgpr_write_b32 a61, 0
	v_accvgpr_write_b32 a62, 0
	v_accvgpr_write_b32 a63, 0
	v_accvgpr_write_b32 a64, 0
	v_accvgpr_write_b32 a65, 0
	v_accvgpr_write_b32 a66, 0
	v_accvgpr_write_b32 a67, 0
	v_accvgpr_write_b32 a68, 0
	v_accvgpr_write_b32 a69, 0
	v_accvgpr_write_b32 a70, 0
	v_accvgpr_write_b32 a71, 0
	v_accvgpr_write_b32 a72, 0
	v_accvgpr_write_b32 a73, 0
	v_accvgpr_write_b32 a74, 0
	v_accvgpr_write_b32 a75, 0
	v_accvgpr_write_b32 a80, 0
	v_accvgpr_write_b32 a81, 0
	v_accvgpr_write_b32 a82, 0
	v_accvgpr_write_b32 a83, 0
	v_accvgpr_write_b32 a76, 0
	v_accvgpr_write_b32 a77, 0
	v_accvgpr_write_b32 a78, 0
	v_accvgpr_write_b32 a79, 0
	v_accvgpr_write_b32 a84, 0
	v_accvgpr_write_b32 a85, 0
	v_accvgpr_write_b32 a86, 0
	v_accvgpr_write_b32 a87, 0
	v_accvgpr_write_b32 a88, 0
	v_accvgpr_write_b32 a89, 0
	v_accvgpr_write_b32 a90, 0
	v_accvgpr_write_b32 a91, 0
	v_accvgpr_write_b32 a96, 0
	v_accvgpr_write_b32 a97, 0
	v_accvgpr_write_b32 a98, 0
	v_accvgpr_write_b32 a99, 0
	v_accvgpr_write_b32 a92, 0
	v_accvgpr_write_b32 a93, 0
	v_accvgpr_write_b32 a94, 0
	v_accvgpr_write_b32 a95, 0
	v_accvgpr_write_b32 a100, 0
	v_accvgpr_write_b32 a101, 0
	v_accvgpr_write_b32 a102, 0
	v_accvgpr_write_b32 a103, 0
	v_accvgpr_write_b32 a108, 0
	v_accvgpr_write_b32 a109, 0
	v_accvgpr_write_b32 a110, 0
	v_accvgpr_write_b32 a111, 0
	v_accvgpr_write_b32 a112, 0
	v_accvgpr_write_b32 a113, 0
	v_accvgpr_write_b32 a114, 0
	v_accvgpr_write_b32 a115, 0
	v_accvgpr_write_b32 a104, 0
	v_accvgpr_write_b32 a105, 0
	v_accvgpr_write_b32 a106, 0
	v_accvgpr_write_b32 a107, 0
	v_accvgpr_write_b32 a116, 0
	v_accvgpr_write_b32 a117, 0
	v_accvgpr_write_b32 a118, 0
	v_accvgpr_write_b32 a119, 0
	v_accvgpr_write_b32 a120, 0
	v_accvgpr_write_b32 a121, 0
	v_accvgpr_write_b32 a122, 0
	v_accvgpr_write_b32 a123, 0
	v_accvgpr_write_b32 a124, 0
	v_accvgpr_write_b32 a125, 0
	v_accvgpr_write_b32 a126, 0
	v_accvgpr_write_b32 a127, 0
	v_mov_b32_e32 v233, 0
	v_mov_b32_e32 v246, 0xf149f2ca
	s_movk_i32 s20, 0x80
	v_lshlrev_b32_e32 v244, 1, v63
	v_mov_b32_e32 v247, 0xf149f2ca
	v_mov_b32_e32 v253, 0xf149f2ca
	v_mov_b32_e32 v198, 0xf149f2ca
	v_mov_b32_e32 v242, 0
	v_mov_b32_e32 v243, 0
	v_mov_b32_e32 v245, 0
	s_waitcnt lgkmcnt(0)
	s_barrier
	s_bitcmp1_b32 s16, 0
	s_cselect_b32 s26, 0x7c00, 0
	s_add_i32 s26, s26, 16
	v_add_u32_e32 v113, s26, v239
	v_lshl_add_u32 v114, v238, 1, v113
	v_add_u32_e32 v113, v113, v240
	ds_read_b128 v[72:75], v114
	ds_read_b128 v[76:79], v114 offset:64
	ds_read_b128 v[48:51], v113 offset:2304
	ds_read_b128 v[52:55], v113 offset:2368
	ds_read_b128 v[56:59], v113 offset:4608
	ds_read_b128 v[60:63], v113 offset:4672
	ds_read_b128 v[40:43], v113 offset:6912
	ds_read_b128 v[64:67], v113 offset:6976
; DI f4 mfma16(h8 a, h8 b, f4 c) { return __builtin_amdgcn_mfma_f32_16x16x32_f16(a, b, c, 0, 0, 0); }
; template <int DQK, bool BIAS>
; __device__ __forceinline__ void attn_pass(const hf* __restrict__ Q, int ldq, const hf* __restrict__ Kp, int ldk, const hf* __restrict__ VT,
;                                           int s0, int L, int q0, float scale_l2, const float* sBias, f4 (&oacc)[8][4], char* smem) {
;     ...
;   for (int kt = 0; kt < nkt; ++kt) {
;     const hf* sK = sbase + (kt & 1) * A_STG; const hf* sVT = sK + 64 * 104;
;     f4 sacc[4][4];
; #pragma unroll
;     for (int mk = 0; mk < 4; ++mk) {
;       h8 kf[NKS];
; #pragma unroll
;       for (int ks = 0; ks < NKS; ++ks) kf[ks] = *(const h8*)(sK + (mk * 16 + fr) * KS + ks * 32 + (fq ^ (((fr >> 2) ^ (fr >> 3)) & 1)) * 8);
; #pragma unroll
;       for (int nq = 0; nq < 4; ++nq) {
;         f4 a = {0.f, 0.f, 0.f, 0.f};
; #pragma unroll
;         for (int ks = 0; ks < NKS; ++ks) a = mfma16(kf[ks], qf[nq][ks], a);
;         sacc[mk][nq] = a;
;       }
;     }
;     if (kt + 1 < nkt) storeKV((kt + 1) & 1);
;     if (kt + 2 < nkt) loadKV(kt + 2);
.LBB0_1948:
	s_bitcmp1_b32 s16, 0
	s_cselect_b32 s17, 0x7c00, 0
	s_add_i32 s95, s17, 16
	s_add_i32 s94, s16, 1
	s_waitcnt lgkmcnt(0)
	v_mfma_f32_16x16x32_f16 v[188:191], v[72:75], v[0:3], 0
	v_mfma_f32_16x16x32_f16 v[188:191], v[76:79], v[4:7], v[188:191]
	v_mfma_f32_16x16x32_f16 v[156:159], v[72:75], v[16:19], 0
	v_mfma_f32_16x16x32_f16 v[172:175], v[72:75], v[8:11], 0
	v_mfma_f32_16x16x32_f16 v[156:159], v[76:79], v[20:23], v[156:159]
	v_mfma_f32_16x16x32_f16 v[124:127], v[72:75], v[24:27], 0
	v_mfma_f32_16x16x32_f16 v[172:175], v[76:79], v[12:15], v[172:175]
	v_mfma_f32_16x16x32_f16 v[124:127], v[76:79], v[28:31], v[124:127]
	s_cmp_ge_u32 s94, s73
	s_cbranch_scc1 .Lqk_noW
	v_mfma_f32_16x16x32_f16 v[184:187], v[48:51], v[0:3], 0
	s_bitcmp1_b32 s94, 0
	s_cselect_b32 s17, 0x7c00, 0
	v_mfma_f32_16x16x32_f16 v[184:187], v[52:55], v[4:7], v[184:187]
	s_add_i32 s17, s17, 16
	v_add3_u32 v68, s17, v211, v244
	v_mfma_f32_16x16x32_f16 v[168:171], v[48:51], v[8:11], 0
	s_waitcnt vmcnt(1)
	ds_write_b128 v68, a[200:203]
	v_mfma_f32_16x16x32_f16 v[168:171], v[52:55], v[12:15], v[168:171]
	s_waitcnt vmcnt(0)
	ds_write_b128 v68, a[204:207] offset:64
	v_mfma_f32_16x16x32_f16 v[152:155], v[48:51], v[16:19], 0
	v_add3_u32 v68, s17, v232, v210
	v_mfma_f32_16x16x32_f16 v[152:155], v[52:55], v[20:23], v[152:155]
	ds_write_b128 v68, a[192:195] offset:13312
	v_mfma_f32_16x16x32_f16 v[120:123], v[48:51], v[24:27], 0
	v_add3_u32 v68, s17, v234, v210
	v_mfma_f32_16x16x32_f16 v[120:123], v[52:55], v[28:31], v[120:123]
	ds_write_b128 v68, a[196:199] offset:13312
	v_mfma_f32_16x16x32_f16 v[180:183], v[56:59], v[0:3], 0
	v_add3_u32 v68, s17, v235, v210
	v_mfma_f32_16x16x32_f16 v[180:183], v[60:63], v[4:7], v[180:183]
	ds_write_b128 v68, a[208:211] offset:13312
	v_mfma_f32_16x16x32_f16 v[164:167], v[56:59], v[8:11], 0
	v_add3_u32 v68, s17, v236, v210
	v_mfma_f32_16x16x32_f16 v[164:167], v[60:63], v[12:15], v[164:167]
	ds_write_b128 v68, a[212:215] offset:13312
	s_branch .Lqk_joinW
.Lqk_noW:
	v_mfma_f32_16x16x32_f16 v[184:187], v[48:51], v[0:3], 0
	v_mfma_f32_16x16x32_f16 v[184:187], v[52:55], v[4:7], v[184:187]
	v_mfma_f32_16x16x32_f16 v[168:171], v[48:51], v[8:11], 0
	v_mfma_f32_16x16x32_f16 v[168:171], v[52:55], v[12:15], v[168:171]
	v_mfma_f32_16x16x32_f16 v[152:155], v[48:51], v[16:19], 0
	v_mfma_f32_16x16x32_f16 v[152:155], v[52:55], v[20:23], v[152:155]
	v_mfma_f32_16x16x32_f16 v[120:123], v[48:51], v[24:27], 0
	v_mfma_f32_16x16x32_f16 v[120:123], v[52:55], v[28:31], v[120:123]
	v_mfma_f32_16x16x32_f16 v[180:183], v[56:59], v[0:3], 0
	v_mfma_f32_16x16x32_f16 v[180:183], v[60:63], v[4:7], v[180:183]
	v_mfma_f32_16x16x32_f16 v[164:167], v[56:59], v[8:11], 0
	v_mfma_f32_16x16x32_f16 v[164:167], v[60:63], v[12:15], v[164:167]
.Lqk_joinW:
	s_add_i32 s16, s16, 2
	s_cmp_ge_u32 s16, s73
	s_cbranch_scc1 .Lqk_noL
	v_mfma_f32_16x16x32_f16 v[148:151], v[56:59], v[16:19], 0
	v_add_u32_e32 v68, s20, v231
	v_mad_i64_i32 v[68:69], s[16:17], v68, s35, v[220:221]
	v_mfma_f32_16x16x32_f16 v[148:151], v[60:63], v[20:23], v[148:151]
	s_lshl_b64 s[16:17], s[20:21], 1
	v_mfma_f32_16x16x32_f16 v[116:119], v[56:59], v[24:27], 0
	global_load_dwordx4 a[200:203], v[68:69], off
	v_mfma_f32_16x16x32_f16 v[176:179], v[40:43], v[0:3], 0
	global_load_dwordx4 a[204:207], v[68:69], off offset:64
	v_mfma_f32_16x16x32_f16 v[176:179], v[64:67], v[4:7], v[176:179]
	v_lshl_add_u64 v[68:69], v[212:213], 0, s[16:17]
	v_mfma_f32_16x16x32_f16 v[160:163], v[40:43], v[8:11], 0
	global_load_dwordx4 a[192:195], v[68:69], off
	v_mfma_f32_16x16x32_f16 v[160:163], v[64:67], v[12:15], v[160:163]
	v_lshl_add_u64 v[68:69], v[214:215], 0, s[16:17]
	v_mfma_f32_16x16x32_f16 v[144:147], v[40:43], v[16:19], 0
	global_load_dwordx4 a[196:199], v[68:69], off
	v_mfma_f32_16x16x32_f16 v[144:147], v[64:67], v[20:23], v[144:147]
	v_lshl_add_u64 v[68:69], v[216:217], 0, s[16:17]
	v_mfma_f32_16x16x32_f16 v[112:115], v[40:43], v[24:27], 0
	global_load_dwordx4 a[208:211], v[68:69], off
	v_mfma_f32_16x16x32_f16 v[116:119], v[60:63], v[28:31], v[116:119]
	v_lshl_add_u64 v[68:69], v[218:219], 0, s[16:17]
	v_mfma_f32_16x16x32_f16 v[112:115], v[64:67], v[28:31], v[112:115]
	global_load_dwordx4 a[212:215], v[68:69], off
	s_branch .LBB0_1952
.Lqk_noL:
	v_mfma_f32_16x16x32_f16 v[148:151], v[56:59], v[16:19], 0
	v_mfma_f32_16x16x32_f16 v[148:151], v[60:63], v[20:23], v[148:151]
	v_mfma_f32_16x16x32_f16 v[116:119], v[56:59], v[24:27], 0
	v_mfma_f32_16x16x32_f16 v[176:179], v[40:43], v[0:3], 0
	v_mfma_f32_16x16x32_f16 v[176:179], v[64:67], v[4:7], v[176:179]
	v_mfma_f32_16x16x32_f16 v[160:163], v[40:43], v[8:11], 0
	v_mfma_f32_16x16x32_f16 v[160:163], v[64:67], v[12:15], v[160:163]
	v_mfma_f32_16x16x32_f16 v[144:147], v[40:43], v[16:19], 0
	v_mfma_f32_16x16x32_f16 v[144:147], v[64:67], v[20:23], v[144:147]
	v_mfma_f32_16x16x32_f16 v[112:115], v[40:43], v[24:27], 0
	v_mfma_f32_16x16x32_f16 v[116:119], v[60:63], v[28:31], v[116:119]
	v_mfma_f32_16x16x32_f16 v[112:115], v[64:67], v[28:31], v[112:115]

; DI f4 mfma16(h8 a, h8 b, f4 c) { return __builtin_amdgcn_mfma_f32_16x16x32_f16(a, b, c, 0, 0, 0); }
; template <int DQK, bool BIAS>
; __device__ __forceinline__ void attn_pass(const hf* __restrict__ Q, int ldq, const hf* __restrict__ Kp, int ldk, const hf* __restrict__ VT,
;                                           int s0, int L, int q0, float scale_l2, const float* sBias, f4 (&oacc)[8][4], char* smem) {
;     ...
;       float ps = 0.f;
; #pragma unroll
;       for (int mk = 0; mk < 4; ++mk)
; #pragma unroll
;         for (int j = 0; j < 4; ++j) {
;           float pe = BIAS ? __builtin_amdgcn_exp2f(sacc[mk][nq][j] - mnew) : __builtin_amdgcn_exp2f(sacc[mk][nq][j] * scale_l2 - mnew);
;           sacc[mk][nq][j] = pe; ps += pe;
;         }
;       lrun[nq] += ps;
; #pragma unroll
;       for (int s2 = 0; s2 < 2; ++s2)
; #pragma unroll
;         for (int i = 0; i < 8; ++i) pf[nq][s2][i] = (hf)sacc[2 * s2 + (i >> 2)][nq][i & 3];
;     }
; #pragma unroll
;     for (int mh = 0; mh < 2; ++mh) {
;       h8 vf[4][2];
; #pragma unroll
;       for (int m4 = 0; m4 < 4; ++m4)
; #pragma unroll
;         for (int s2 = 0; s2 < 2; ++s2) {
;           h4 v0 = *(const h4*)(sVT + ((mh * 4 + m4) * 16 + fr) * 72 + s2 * 32 + fq * 4);
;           h4 v1 = *(const h4*)(sVT + ((mh * 4 + m4) * 16 + fr) * 72 + s2 * 32 + 16 + fq * 4);
;           vf[m4][s2] = __builtin_shufflevector(v0, v1, 0, 1, 2, 3, 4, 5, 6, 7);
;         }
; #pragma unroll
;       for (int nq = 0; nq < 4; ++nq)
; #pragma unroll
;         for (int m4 = 0; m4 < 4; ++m4) {
;           oacc[mh * 4 + m4][nq] = mfma16(vf[m4][0], pf[nq][0], oacc[mh * 4 + m4][nq]);
;           oacc[mh * 4 + m4][nq] = mfma16(vf[m4][1], pf[nq][1], oacc[mh * 4 + m4][nq]);
;         }
.LBB0_1976:
	v_lshlrev_b32_e32 v113, 1, v238
	v_lshlrev_b32_e32 v114, 1, v237
	v_add3_u32 v113, s95, v113, v114
	v_add_u32_e32 v114, 0x3000, v113
	ds_read2_b64 a[128:131], v114 offset0:128 offset1:132
	v_add_u32_e32 v114, 0x3000, v113
	ds_read2_b64 a[132:135], v114 offset0:136 offset1:140
	v_sub_f32_e32 v48, v128, v144
	v_exp_f32_e32 v48, v48
	v_sub_f32_e32 v50, v129, v144
	v_exp_f32_e32 v50, v50
	v_add_u32_e32 v114, 0x3800, v113
	ds_read2_b64 a[136:139], v114 offset0:160 offset1:164
	v_sub_f32_e32 v51, v130, v144
	v_exp_f32_e32 v51, v51
	v_sub_f32_e32 v52, v131, v144
	v_exp_f32_e32 v52, v52
	v_add_u32_e32 v114, 0x3800, v113
	ds_read2_b64 a[140:143], v114 offset0:168 offset1:172
	v_sub_f32_e32 v53, v140, v144
	v_add_f32_e32 v49, 0, v48
	v_exp_f32_e32 v53, v53
	v_sub_f32_e32 v54, v141, v144
	v_add_u32_e32 v114, 0x4000, v113
	ds_read2_b64 a[144:147], v114 offset0:192 offset1:196
	v_add_f32_e32 v49, v50, v49
	v_exp_f32_e32 v54, v54
	v_sub_f32_e32 v55, v142, v144
	v_add_f32_e32 v49, v51, v49
	v_add_u32_e32 v114, 0x4000, v113
	ds_read2_b64 a[148:151], v114 offset0:200 offset1:204
	v_exp_f32_e32 v55, v55
	v_sub_f32_e32 v56, v143, v144
	v_add_f32_e32 v49, v52, v49
	v_exp_f32_e32 v56, v56
	v_add_u32_e32 v114, 0x4800, v113
	ds_read2_b64 a[152:155], v114 offset0:224 offset1:228
	v_sub_f32_e32 v57, v136, v144
	v_add_f32_e32 v49, v53, v49
	v_exp_f32_e32 v57, v57
	v_sub_f32_e32 v58, v137, v144
	v_add_u32_e32 v114, 0x4800, v113
	ds_read2_b64 a[156:159], v114 offset0:232 offset1:236
	v_add_f32_e32 v49, v54, v49
	v_exp_f32_e32 v58, v58
	v_sub_f32_e32 v59, v138, v144
	v_add_f32_e32 v49, v55, v49
	v_add_u32_e32 v114, 0x5800, v113
	ds_read2_b64 a[160:163], v114 offset1:4
	v_exp_f32_e32 v59, v59
	v_sub_f32_e32 v60, v139, v144
	v_add_f32_e32 v49, v56, v49
	v_exp_f32_e32 v60, v60
	v_add_u32_e32 v114, 0x5800, v113
	ds_read2_b64 a[164:167], v114 offset0:8 offset1:12
	v_sub_f32_e32 v61, v132, v144
	v_add_f32_e32 v49, v57, v49
	v_exp_f32_e32 v61, v61
	v_sub_f32_e32 v62, v133, v144
	v_add_u32_e32 v114, 0x6000, v113
	ds_read2_b64 a[168:171], v114 offset0:32 offset1:36
	v_add_f32_e32 v49, v58, v49
	v_exp_f32_e32 v62, v62
	v_sub_f32_e32 v63, v134, v144
	v_add_f32_e32 v49, v59, v49
	v_add_u32_e32 v114, 0x6000, v113
	ds_read2_b64 a[172:175], v114 offset0:40 offset1:44
	v_exp_f32_e32 v63, v63
	v_sub_f32_e32 v64, v135, v144
	v_add_f32_e32 v49, v60, v49
	v_exp_f32_e32 v64, v64
	v_add_u32_e32 v114, 0x6800, v113
	ds_read2_b64 a[176:179], v114 offset0:64 offset1:68
	v_add_f32_e32 v49, v61, v49
	v_add_f32_e32 v49, v62, v49
	v_add_f32_e32 v49, v63, v49
	v_cvt_pk_f16_f32 v55, v55, v56
	v_add_u32_e32 v114, 0x6800, v113
	ds_read2_b64 a[180:183], v114 offset0:72 offset1:76
	v_add_f32_e32 v49, v64, v49
	v_cvt_pk_f16_f32 v54, v53, v54
	v_cvt_pk_f16_f32 v53, v51, v52
	v_cvt_pk_f16_f32 v52, v48, v50
	v_add_u32_e32 v114, 0x7000, v113
	ds_read2_b64 a[184:187], v114 offset0:96 offset1:100
	v_cvt_pk_f16_f32 v48, v57, v58
	v_add_f32_e32 v242, v49, v242
	v_cvt_pk_f16_f32 v49, v59, v60
	v_cvt_pk_f16_f32 v50, v61, v62
	v_add_u32_e32 v114, 0x7000, v113
	ds_read2_b64 a[188:191], v114 offset0:104 offset1:108
	v_cvt_pk_f16_f32 v51, v63, v64
	v_sub_f32_e32 v56, v80, v160
	v_exp_f32_e32 v56, v56
	s_waitcnt lgkmcnt(0)
	v_mfma_f32_16x16x32_f16 a[12:15], a[128:131], v[52:55], a[12:15]
	v_sub_f32_e32 v58, v81, v160
	v_exp_f32_e32 v58, v58
	v_mfma_f32_16x16x32_f16 a[28:31], a[136:139], v[52:55], a[28:31]
	v_sub_f32_e32 v59, v82, v160
	v_exp_f32_e32 v59, v59
	v_mfma_f32_16x16x32_f16 a[40:43], a[144:147], v[52:55], a[40:43]
	v_sub_f32_e32 v60, v83, v160
	v_exp_f32_e32 v60, v60
	v_mfma_f32_16x16x32_f16 a[56:59], a[152:155], v[52:55], a[56:59]
	v_sub_f32_e32 v61, v92, v160
	v_add_f32_e32 v57, 0, v56
	v_mfma_f32_16x16x32_f16 a[12:15], a[132:135], v[48:51], a[12:15]
	v_exp_f32_e32 v61, v61
	v_sub_f32_e32 v62, v93, v160
	v_mfma_f32_16x16x32_f16 a[28:31], a[140:143], v[48:51], a[28:31]
	v_add_f32_e32 v57, v58, v57
	v_exp_f32_e32 v62, v62
	v_mfma_f32_16x16x32_f16 a[40:43], a[148:151], v[48:51], a[40:43]
	v_sub_f32_e32 v63, v94, v160
	v_add_f32_e32 v57, v59, v57
	v_mfma_f32_16x16x32_f16 a[56:59], a[156:159], v[48:51], a[56:59]
	v_exp_f32_e32 v63, v63
	v_sub_f32_e32 v64, v95, v160
	v_mfma_f32_16x16x32_f16 a[72:75], a[160:163], v[52:55], a[72:75]
	v_sub_f32_e32 v32, v32, v176
	v_add_f32_e32 v57, v60, v57
	v_mfma_f32_16x16x32_f16 a[88:91], a[168:171], v[52:55], a[88:91]
	v_exp_f32_e32 v64, v64
	v_exp_f32_e32 v32, v32
	v_mfma_f32_16x16x32_f16 a[108:111], a[176:179], v[52:55], a[108:111]
	v_sub_f32_e32 v33, v33, v176
	v_add_f32_e32 v57, v61, v57
	v_mfma_f32_16x16x32_f16 a[120:123], a[184:187], v[52:55], a[120:123]
	v_exp_f32_e32 v33, v33
	v_sub_f32_e32 v34, v34, v176
	v_mfma_f32_16x16x32_f16 a[72:75], a[164:167], v[48:51], a[72:75]
	v_add_f32_e32 v57, v62, v57
	v_exp_f32_e32 v34, v34
	v_mfma_f32_16x16x32_f16 a[88:91], a[172:175], v[48:51], a[88:91]
	v_sub_f32_e32 v35, v35, v176
	v_add_f32_e32 v57, v63, v57
	v_mfma_f32_16x16x32_f16 a[108:111], a[180:183], v[48:51], a[108:111]
	v_exp_f32_e32 v35, v35
	v_sub_f32_e32 v44, v44, v176
	v_mfma_f32_16x16x32_f16 a[120:123], a[188:191], v[48:51], a[120:123]
	v_add_f32_e32 v57, v64, v57
	v_sub_f32_e32 v65, v84, v160
	v_sub_f32_e32 v66, v85, v160
	v_cvt_pk_f16_f32 v63, v63, v64
	v_add_f32_e32 v64, 0, v32
	v_exp_f32_e32 v44, v44
	v_sub_f32_e32 v45, v45, v176
	v_exp_f32_e32 v65, v65
	v_exp_f32_e32 v66, v66
	v_add_f32_e32 v64, v33, v64
	v_exp_f32_e32 v45, v45
	v_sub_f32_e32 v46, v46, v176
	v_add_f32_e32 v64, v34, v64
	v_exp_f32_e32 v46, v46
	v_sub_f32_e32 v47, v47, v176
	v_add_f32_e32 v64, v35, v64
	v_exp_f32_e32 v47, v47
	v_sub_f32_e32 v40, v40, v176
	v_add_f32_e32 v64, v44, v64
; DI f4 mfma16(h8 a, h8 b, f4 c) { return __builtin_amdgcn_mfma_f32_16x16x32_f16(a, b, c, 0, 0, 0); }
; template <int DQK, bool BIAS>
; __device__ __forceinline__ void attn_pass(const hf* __restrict__ Q, int ldq, const hf* __restrict__ Kp, int ldk, const hf* __restrict__ VT,
;                                           int s0, int L, int q0, float scale_l2, const float* sBias, f4 (&oacc)[8][4], char* smem) {
;     ...
;       float ps = 0.f;
; #pragma unroll
;       for (int mk = 0; mk < 4; ++mk)
; #pragma unroll
;         for (int j = 0; j < 4; ++j) {
;           float pe = BIAS ? __builtin_amdgcn_exp2f(sacc[mk][nq][j] - mnew) : __builtin_amdgcn_exp2f(sacc[mk][nq][j] * scale_l2 - mnew);
;           sacc[mk][nq][j] = pe; ps += pe;
;         }
;       lrun[nq] += ps;
; #pragma unroll
;       for (int s2 = 0; s2 < 2; ++s2)
; #pragma unroll
;         for (int i = 0; i < 8; ++i) pf[nq][s2][i] = (hf)sacc[2 * s2 + (i >> 2)][nq][i & 3];
;     }
; #pragma unroll
;     for (int mh = 0; mh < 2; ++mh) {
;       h8 vf[4][2];
; #pragma unroll
;       for (int m4 = 0; m4 < 4; ++m4)
; #pragma unroll
;         for (int s2 = 0; s2 < 2; ++s2) {
;           h4 v0 = *(const h4*)(sVT + ((mh * 4 + m4) * 16 + fr) * 72 + s2 * 32 + fq * 4);
;           h4 v1 = *(const h4*)(sVT + ((mh * 4 + m4) * 16 + fr) * 72 + s2 * 32 + 16 + fq * 4);
;           vf[m4][s2] = __builtin_shufflevector(v0, v1, 0, 1, 2, 3, 4, 5, 6, 7);
;         }
; #pragma unroll
;       for (int nq = 0; nq < 4; ++nq)
; #pragma unroll
;         for (int m4 = 0; m4 < 4; ++m4) {
;           oacc[mh * 4 + m4][nq] = mfma16(vf[m4][0], pf[nq][0], oacc[mh * 4 + m4][nq]);
;           oacc[mh * 4 + m4][nq] = mfma16(vf[m4][1], pf[nq][1], oacc[mh * 4 + m4][nq]);
;         }
;     }
;     __syncthreads();
	v_exp_f32_e32 v40, v40
	v_sub_f32_e32 v41, v41, v176
	v_add_f32_e32 v57, v65, v57
	v_cvt_pk_f16_f32 v62, v61, v62
	v_cvt_pk_f16_f32 v61, v59, v60
	v_cvt_pk_f16_f32 v60, v56, v58
	v_cvt_pk_f16_f32 v56, v65, v66
	v_add_f32_e32 v64, v45, v64
	v_exp_f32_e32 v65, v41
	v_add_f32_e32 v64, v46, v64
	v_add_f32_e32 v64, v47, v64
	v_add_f32_e32 v64, v40, v64
	v_sub_f32_e32 v42, v42, v176
	v_add_f32_e32 v41, v65, v64
	v_exp_f32_e32 v64, v42
	v_sub_f32_e32 v42, v43, v176
	v_add_f32_e32 v57, v66, v57
	v_exp_f32_e32 v66, v42
	v_sub_f32_e32 v36, v36, v176
	v_sub_f32_e32 v37, v37, v176
	v_exp_f32_e32 v36, v36
	v_exp_f32_e32 v37, v37
	v_sub_f32_e32 v38, v38, v176
	v_sub_f32_e32 v39, v39, v176
	v_cvt_pk_f16_f32 v47, v46, v47
	v_cvt_pk_f16_f32 v46, v44, v45
	v_cvt_pk_f16_f32 v44, v32, v33
	v_add_f32_e32 v41, v64, v41
	v_exp_f32_e32 v38, v38
	v_exp_f32_e32 v39, v39
	v_cvt_pk_f16_f32 v45, v34, v35
	v_add_f32_e32 v41, v66, v41
	v_add_f32_e32 v41, v36, v41
	v_cvt_pk_f16_f32 v42, v36, v37
	v_add_f32_e32 v41, v37, v41
	v_add_f32_e32 v41, v38, v41
	v_cvt_pk_f16_f32 v43, v38, v39
	v_add_f32_e32 v41, v39, v41
	v_add_f32_e32 v245, v41, v245
	v_cvt_pk_f16_f32 v41, v64, v66
	v_cvt_pk_f16_f32 v40, v40, v65
	v_sub_f32_e32 v67, v86, v160
	v_exp_f32_e32 v67, v67
	v_mfma_f32_16x16x32_f16 a[0:3], a[128:131], v[44:47], a[0:3]
	v_sub_f32_e32 v68, v87, v160
	v_exp_f32_e32 v68, v68
	v_mfma_f32_16x16x32_f16 a[8:11], a[136:139], v[44:47], a[8:11]
	v_sub_f32_e32 v69, v88, v160
	v_exp_f32_e32 v69, v69
	v_mfma_f32_16x16x32_f16 a[24:27], a[144:147], v[44:47], a[24:27]
	v_sub_f32_e32 v70, v89, v160
	v_exp_f32_e32 v70, v70
	v_mfma_f32_16x16x32_f16 a[44:47], a[152:155], v[44:47], a[44:47]
	v_sub_f32_e32 v71, v90, v160
	v_add_f32_e32 v57, v67, v57
	v_mfma_f32_16x16x32_f16 a[0:3], a[132:135], v[40:43], a[0:3]
	v_exp_f32_e32 v71, v71
	v_sub_f32_e32 v72, v91, v160
	v_mfma_f32_16x16x32_f16 a[8:11], a[140:143], v[40:43], a[8:11]
	v_add_f32_e32 v57, v68, v57
	v_exp_f32_e32 v72, v72
	v_mfma_f32_16x16x32_f16 a[24:27], a[148:151], v[40:43], a[24:27]
	v_add_f32_e32 v57, v69, v57
	v_add_f32_e32 v57, v70, v57
	v_mfma_f32_16x16x32_f16 a[44:47], a[156:159], v[40:43], a[44:47]
	v_add_f32_e32 v57, v71, v57
	v_add_f32_e32 v57, v72, v57
	v_mfma_f32_16x16x32_f16 a[64:67], a[160:163], v[44:47], a[64:67]
	v_add_f32_e32 v243, v57, v243
	v_cvt_pk_f16_f32 v57, v67, v68
	v_mfma_f32_16x16x32_f16 a[76:79], a[168:171], v[44:47], a[76:79]
	v_cvt_pk_f16_f32 v58, v69, v70
	v_cvt_pk_f16_f32 v59, v71, v72
	v_mfma_f32_16x16x32_f16 a[92:95], a[176:179], v[44:47], a[92:95]
	v_sub_f32_e32 v32, v96, v112
	v_exp_f32_e32 v32, v32
	v_mfma_f32_16x16x32_f16 a[104:107], a[184:187], v[44:47], a[104:107]
	v_sub_f32_e32 v34, v97, v112
	v_exp_f32_e32 v34, v34
	v_mfma_f32_16x16x32_f16 a[64:67], a[164:167], v[40:43], a[64:67]
	v_sub_f32_e32 v35, v98, v112
	v_exp_f32_e32 v35, v35
	v_mfma_f32_16x16x32_f16 a[76:79], a[172:175], v[40:43], a[76:79]
	v_sub_f32_e32 v36, v99, v112
	v_exp_f32_e32 v36, v36
	v_mfma_f32_16x16x32_f16 a[92:95], a[180:183], v[40:43], a[92:95]
	v_sub_f32_e32 v37, v104, v112
	v_add_f32_e32 v33, 0, v32
	v_mfma_f32_16x16x32_f16 a[104:107], a[188:191], v[40:43], a[104:107]
	v_exp_f32_e32 v37, v37
	v_sub_f32_e32 v38, v105, v112
	v_mfma_f32_16x16x32_f16 a[4:7], a[128:131], v[60:63], a[4:7]
	v_add_f32_e32 v33, v34, v33
	v_exp_f32_e32 v38, v38
	v_mfma_f32_16x16x32_f16 a[16:19], a[136:139], v[60:63], a[16:19]
	v_sub_f32_e32 v39, v106, v112
	v_add_f32_e32 v33, v35, v33
	v_mfma_f32_16x16x32_f16 a[36:39], a[144:147], v[60:63], a[36:39]
	v_exp_f32_e32 v39, v39
	v_sub_f32_e32 v64, v107, v112
	v_mfma_f32_16x16x32_f16 a[52:55], a[152:155], v[60:63], a[52:55]
	v_add_f32_e32 v33, v36, v33
	v_exp_f32_e32 v64, v64
	v_mfma_f32_16x16x32_f16 a[4:7], a[132:135], v[56:59], a[4:7]
	v_sub_f32_e32 v65, v100, v112
	v_add_f32_e32 v33, v37, v33
	v_mfma_f32_16x16x32_f16 a[16:19], a[140:143], v[56:59], a[16:19]
	v_exp_f32_e32 v65, v65
	v_sub_f32_e32 v66, v101, v112
	v_mfma_f32_16x16x32_f16 a[36:39], a[148:151], v[56:59], a[36:39]
	v_add_f32_e32 v33, v38, v33
	v_exp_f32_e32 v66, v66
	v_mfma_f32_16x16x32_f16 a[52:55], a[156:159], v[56:59], a[52:55]
	v_sub_f32_e32 v67, v102, v112
	v_add_f32_e32 v33, v39, v33
	v_mfma_f32_16x16x32_f16 a[68:71], a[160:163], v[60:63], a[68:71]
	v_exp_f32_e32 v67, v67
	v_sub_f32_e32 v68, v103, v112
	v_mfma_f32_16x16x32_f16 a[84:87], a[168:171], v[60:63], a[84:87]
	v_add_f32_e32 v33, v64, v33
	v_exp_f32_e32 v68, v68
	v_mfma_f32_16x16x32_f16 a[100:103], a[176:179], v[60:63], a[100:103]
	v_sub_f32_e32 v69, v108, v112
	v_add_f32_e32 v33, v65, v33
	v_mfma_f32_16x16x32_f16 a[116:119], a[184:187], v[60:63], a[116:119]
	v_exp_f32_e32 v69, v69
	v_sub_f32_e32 v70, v109, v112
	v_mfma_f32_16x16x32_f16 a[68:71], a[164:167], v[56:59], a[68:71]
	v_add_f32_e32 v33, v66, v33
	v_exp_f32_e32 v70, v70
	v_mfma_f32_16x16x32_f16 a[84:87], a[172:175], v[56:59], a[84:87]
	v_sub_f32_e32 v71, v110, v112
	v_add_f32_e32 v33, v67, v33
	v_mfma_f32_16x16x32_f16 a[100:103], a[180:183], v[56:59], a[100:103]
	v_exp_f32_e32 v71, v71
	v_sub_f32_e32 v72, v111, v112
	v_mfma_f32_16x16x32_f16 a[116:119], a[188:191], v[56:59], a[116:119]
	v_add_f32_e32 v33, v68, v33
	v_exp_f32_e32 v72, v72
	v_add_f32_e32 v33, v69, v33
	v_add_f32_e32 v33, v70, v33
	v_cvt_pk_f16_f32 v39, v39, v64
	v_cvt_pk_f16_f32 v38, v37, v38
	v_cvt_pk_f16_f32 v37, v35, v36
	v_cvt_pk_f16_f32 v36, v32, v34
	v_cvt_pk_f16_f32 v32, v65, v66
	v_add_f32_e32 v33, v71, v33
	v_add_f32_e32 v33, v72, v33
	v_add_f32_e32 v233, v33, v233
	v_cvt_pk_f16_f32 v35, v71, v72
	v_cvt_pk_f16_f32 v34, v69, v70
	v_cvt_pk_f16_f32 v33, v67, v68
	s_nop 1
	s_waitcnt lgkmcnt(0)
	s_barrier
; DI f4 mfma16(h8 a, h8 b, f4 c) { return __builtin_amdgcn_mfma_f32_16x16x32_f16(a, b, c, 0, 0, 0); }
; template <int DQK, bool BIAS>
; __device__ __forceinline__ void attn_pass(const hf* __restrict__ Q, int ldq, const hf* __restrict__ Kp, int ldk, const hf* __restrict__ VT,
;                                           int s0, int L, int q0, float scale_l2, const float* sBias, f4 (&oacc)[8][4], char* smem) {
;     ...
;       for (int ks = 0; ks < NKS; ++ks) kf[ks] = *(const h8*)(sK + (mk * 16 + fr) * KS + ks * 32 + (fq ^ (((fr >> 2) ^ (fr >> 3)) & 1)) * 8);
;     ...
;           h4 v0 = *(const h4*)(sVT + ((mh * 4 + m4) * 16 + fr) * 72 + s2 * 32 + fq * 4);
;           h4 v1 = *(const h4*)(sVT + ((mh * 4 + m4) * 16 + fr) * 72 + s2 * 32 + 16 + fq * 4);
;           vf[m4][s2] = __builtin_shufflevector(v0, v1, 0, 1, 2, 3, 4, 5, 6, 7);
;         }
; #pragma unroll
;       for (int nq = 0; nq < 4; ++nq)
; #pragma unroll
;         for (int m4 = 0; m4 < 4; ++m4) {
;           oacc[mh * 4 + m4][nq] = mfma16(vf[m4][0], pf[nq][0], oacc[mh * 4 + m4][nq]);
;           oacc[mh * 4 + m4][nq] = mfma16(vf[m4][1], pf[nq][1], oacc[mh * 4 + m4][nq]);
;         }
;     }
;     __syncthreads();
	s_bitcmp1_b32 s94, 0
	s_cselect_b32 s26, 0x7c00, 0
	s_add_i32 s26, s26, 16
	v_add_u32_e32 v113, s26, v239
	v_lshl_add_u32 v114, v238, 1, v113
	v_add_u32_e32 v113, v113, v240
	ds_read_b128 v[72:75], v114
	ds_read_b128 v[76:79], v114 offset:64
	ds_read_b128 v[48:51], v113 offset:2304
	ds_read_b128 v[52:55], v113 offset:2368
	ds_read_b128 v[56:59], v113 offset:4608
	ds_read_b128 v[60:63], v113 offset:4672
	ds_read_b128 v[40:43], v113 offset:6912
	ds_read_b128 v[64:67], v113 offset:6976
	v_mfma_f32_16x16x32_f16 a[20:23], a[128:131], v[36:39], a[20:23]
	v_mfma_f32_16x16x32_f16 a[32:35], a[136:139], v[36:39], a[32:35]
	v_mfma_f32_16x16x32_f16 a[48:51], a[144:147], v[36:39], a[48:51]
	v_mfma_f32_16x16x32_f16 a[60:63], a[152:155], v[36:39], a[60:63]
	v_mfma_f32_16x16x32_f16 a[20:23], a[132:135], v[32:35], a[20:23]
	v_mfma_f32_16x16x32_f16 a[32:35], a[140:143], v[32:35], a[32:35]
	v_mfma_f32_16x16x32_f16 a[48:51], a[148:151], v[32:35], a[48:51]
	v_mfma_f32_16x16x32_f16 a[60:63], a[156:159], v[32:35], a[60:63]
	v_mfma_f32_16x16x32_f16 a[80:83], a[160:163], v[36:39], a[80:83]
	v_mfma_f32_16x16x32_f16 a[96:99], a[168:171], v[36:39], a[96:99]
	v_mfma_f32_16x16x32_f16 a[112:115], a[176:179], v[36:39], a[112:115]
	v_mfma_f32_16x16x32_f16 a[124:127], a[184:187], v[36:39], a[124:127]
	v_mfma_f32_16x16x32_f16 a[80:83], a[164:167], v[32:35], a[80:83]
	v_mfma_f32_16x16x32_f16 a[96:99], a[172:175], v[32:35], a[96:99]
	v_mfma_f32_16x16x32_f16 a[112:115], a[180:183], v[32:35], a[112:115]
	v_mfma_f32_16x16x32_f16 a[124:127], a[188:191], v[32:35], a[124:127]
	s_add_i32 s20, s20, 64
	s_cmp_lg_u32 s73, s94
	s_cbranch_scc0 .LBB0_1978
	v_mov_b32_e32 v246, v112
	v_mov_b32_e32 v247, v144
	v_mov_b32_e32 v253, v160
	v_mov_b32_e32 v198, v176
	s_mov_b32 s16, s94
	s_branch .LBB0_1948

; template <int DQK, bool BIAS>
; __device__ __forceinline__ void attn_pass(const hf* __restrict__ Q, int ldq, const hf* __restrict__ Kp, int ldk, const hf* __restrict__ VT,
;                                           int s0, int L, int q0, float scale_l2, const float* sBias, f4 (&oacc)[8][4], char* smem) {
;     ...
; #pragma unroll
;   for (int nq = 0; nq < 4; ++nq) {
;     float lt = lrun[nq]; lt += shx(lt, 16); lt += shx(lt, 32);
;     const float inv = 1.f / lt;
; #pragma unroll
;     for (int md = 0; md < 8; ++md) { oacc[md][nq][0] *= inv; oacc[md][nq][1] *= inv; oacc[md][nq][2] *= inv; oacc[md][nq][3] *= inv; }
;   }
.LBB0_1978:
	s_waitcnt lgkmcnt(0)
	ds_swizzle_b32 v60, v245 offset:swizzle(SWAP,16)
	v_accvgpr_read_b32 v52, a64
	v_accvgpr_read_b32 v55, a67
	v_accvgpr_read_b32 v103, a3
	v_accvgpr_read_b32 v64, a104
	s_waitcnt lgkmcnt(0)
	v_add_f32_e32 v68, v245, v60
	v_mov_b32_e32 v60, v224
	v_accvgpr_read_b32 v89, a79
	v_lshlrev_b32_e32 v60, 2, v60
	v_bitop3_b32 v60, v60, s3, v226 bitop3:0x6c
	ds_bpermute_b32 v69, v60, v68
	v_accvgpr_read_b32 v63, a47
	v_accvgpr_read_b32 v85, a11
	v_accvgpr_read_b32 v102, a2
	v_accvgpr_read_b32 v101, a1
	s_waitcnt lgkmcnt(0)
	v_add_f32_e32 v76, v68, v69
	v_div_scale_f32 v77, s[16:17], v76, v76, 1.0
	v_rcp_f32_e32 v94, v77
	v_accvgpr_read_b32 v71, a27
	v_accvgpr_read_b32 v65, a105
	v_accvgpr_read_b32 v66, a106
	v_fma_f32 v95, -v77, v94, 1.0
	v_fmac_f32_e32 v94, v95, v94
	v_div_scale_f32 v95, vcc, 1.0, v76, 1.0
	v_mul_f32_e32 v108, v95, v94
	v_fma_f32 v109, -v77, v108, v95
	v_fmac_f32_e32 v108, v109, v94
	v_fma_f32 v77, -v77, v108, v95
	v_div_fmas_f32 v77, v77, v94, v108
	v_div_fixup_f32 v94, v77, v76, 1.0
	v_mul_f32_e32 v138, v55, v94
	ds_swizzle_b32 v55, v243 offset:swizzle(SWAP,16)
	v_mul_f32_e32 v141, v63, v94
	v_mov_b32_e32 v63, v224
	v_mul_f32_e32 v145, v71, v94
	v_lshlrev_b32_e32 v63, 2, v63
	s_waitcnt lgkmcnt(0)
	v_add_f32_e32 v55, v243, v55
	v_bitop3_b32 v63, v63, s3, v226 bitop3:0x6c
	ds_bpermute_b32 v63, v63, v55
	v_accvgpr_read_b32 v86, a76
	v_accvgpr_read_b32 v53, a65
	v_accvgpr_read_b32 v54, a66
	v_accvgpr_read_b32 v62, a46
	s_waitcnt lgkmcnt(0)
	v_add_f32_e32 v55, v55, v63
	v_div_scale_f32 v63, s[16:17], v55, v55, 1.0
	v_rcp_f32_e32 v71, v63
	v_accvgpr_read_b32 v61, a45
	v_accvgpr_read_b32 v60, a44
	v_accvgpr_read_b32 v70, a26
	v_accvgpr_read_b32 v69, a25
	v_accvgpr_read_b32 v68, a24
	v_accvgpr_read_b32 v84, a10
	v_accvgpr_read_b32 v83, a9
	v_mov_b32_e32 v76, v101
	v_mov_b32_e32 v77, v102
	v_accvgpr_read_b32 v88, a78
	v_accvgpr_read_b32 v100, a0
	v_pk_mul_f32 v[118:119], v[76:77], v[94:95] op_sel_hi:[1,0]
	v_mov_b32_e32 v76, v83
	v_mov_b32_e32 v77, v84
	v_mul_f32_e32 v84, v68, v94
	v_mov_b32_e32 v68, v69
	v_mov_b32_e32 v69, v70
	v_mul_f32_e32 v70, v60, v94
	v_mov_b32_e32 v60, v61
	v_mov_b32_e32 v61, v62
	v_mul_f32_e32 v62, v52, v94
	v_mov_b32_e32 v52, v53
	v_mov_b32_e32 v53, v54
	v_mul_f32_e32 v54, v86, v94
	v_mul_f32_e32 v86, v64, v94
	v_mov_b32_e32 v64, v65
	v_mov_b32_e32 v65, v66
	v_mul_f32_e32 v116, v100, v94
	v_pk_mul_f32 v[100:101], v[76:77], v[94:95] op_sel_hi:[1,0]
	v_pk_mul_f32 v[76:77], v[68:69], v[94:95] op_sel_hi:[1,0]
	v_pk_mul_f32 v[68:69], v[60:61], v[94:95] op_sel_hi:[1,0]
	v_pk_mul_f32 v[60:61], v[52:53], v[94:95] op_sel_hi:[1,0]
	v_mov_b32_e32 v53, v88
	v_mul_f32_e32 v152, v89, v94
	v_pk_mul_f32 v[88:89], v[64:65], v[94:95] op_sel_hi:[1,0]
	v_fma_f32 v64, -v63, v71, 1.0
	v_fmac_f32_e32 v71, v64, v71
	v_div_scale_f32 v64, vcc, 1.0, v55, 1.0
	v_mul_f32_e32 v65, v64, v71
	v_fma_f32 v66, -v63, v65, v64
	v_fmac_f32_e32 v65, v66, v71
	v_fma_f32 v63, -v63, v65, v64
	v_div_fmas_f32 v63, v63, v71, v65
	v_accvgpr_read_b32 v56, a68
	v_div_fixup_f32 v136, v63, v55, 1.0
	ds_swizzle_b32 v55, v242 offset:swizzle(SWAP,16)
	v_accvgpr_read_b32 v59, a71
	v_mul_f32_e32 v139, v59, v136
	v_mov_b32_e32 v59, v224
	s_waitcnt lgkmcnt(0)
	v_add_f32_e32 v55, v242, v55
	v_lshlrev_b32_e32 v59, 2, v59
	v_bitop3_b32 v59, v59, s3, v226 bitop3:0x6c
	ds_bpermute_b32 v59, v59, v55
	v_accvgpr_read_b32 v67, a107
	v_accvgpr_read_b32 v157, a7
	v_mul_f32_e32 v147, v67, v94
	v_accvgpr_read_b32 v72, a92
	s_waitcnt lgkmcnt(0)
	v_add_f32_e32 v55, v55, v59
	v_div_scale_f32 v59, s[16:17], v55, v55, 1.0
	v_rcp_f32_e32 v63, v59
	v_accvgpr_read_b32 v113, a19
	v_accvgpr_read_b32 v156, a6
	v_accvgpr_read_b32 v155, a5
	v_fma_f32 v67, -v59, v63, 1.0
	v_fmac_f32_e32 v63, v67, v63
	v_div_scale_f32 v67, vcc, 1.0, v55, 1.0
	v_accvgpr_read_b32 v75, a95
	v_accvgpr_read_b32 v93, a39
	v_accvgpr_read_b32 v112, a18
	v_accvgpr_read_b32 v111, a17
	v_mov_b32_e32 v64, v155
	v_mov_b32_e32 v65, v156
	v_mul_f32_e32 v71, v67, v63
	v_accvgpr_read_b32 v96, a100
	v_accvgpr_read_b32 v73, a93
	v_accvgpr_read_b32 v74, a94
	v_accvgpr_read_b32 v87, a77
	v_accvgpr_read_b32 v131, a55
	v_accvgpr_read_b32 v92, a38
	v_accvgpr_read_b32 v91, a37
	v_accvgpr_read_b32 v110, a16
	v_accvgpr_read_b32 v82, a8
	v_mul_f32_e32 v153, v75, v94
	v_pk_mul_f32 v[126:127], v[64:65], v[136:137] op_sel_hi:[1,0]
	v_mov_b32_e32 v64, v111
	v_mov_b32_e32 v65, v112
	v_fma_f32 v75, -v59, v71, v67
	v_accvgpr_read_b32 v78, a116
	v_accvgpr_read_b32 v97, a101
	v_accvgpr_read_b32 v98, a102
	v_accvgpr_read_b32 v107, a87
	v_accvgpr_read_b32 v57, a69
	v_accvgpr_read_b32 v58, a70
	v_accvgpr_read_b32 v130, a54
	v_accvgpr_read_b32 v129, a53
	v_accvgpr_read_b32 v90, a36
	v_mul_f32_e32 v108, v82, v94
	v_mov_b32_e32 v52, v87
	v_mul_f32_e32 v82, v72, v94
	v_mov_b32_e32 v72, v73
	v_mov_b32_e32 v73, v74
	v_mul_f32_e32 v114, v110, v136
	v_pk_mul_f32 v[110:111], v[64:65], v[136:137] op_sel_hi:[1,0]
	v_mov_b32_e32 v64, v91
	v_mov_b32_e32 v65, v92
	v_fmac_f32_e32 v71, v75, v63
	v_accvgpr_read_b32 v79, a117
	v_accvgpr_read_b32 v80, a118
	v_accvgpr_read_b32 v106, a86
	v_accvgpr_read_b32 v105, a85
	v_accvgpr_read_b32 v123, a15
	v_mul_f32_e32 v160, v103, v94
	v_mul_f32_e32 v151, v85, v94
	v_pk_mul_f32 v[52:53], v[52:53], v[94:95] op_sel_hi:[1,0]
	v_pk_mul_f32 v[102:103], v[72:73], v[94:95] op_sel_hi:[1,0]
	v_mul_f32_e32 v94, v90, v136
	v_pk_mul_f32 v[90:91], v[64:65], v[136:137] op_sel_hi:[1,0]
	v_mov_b32_e32 v64, v129
	v_mov_b32_e32 v65, v130
	v_mul_f32_e32 v66, v56, v136
	v_mov_b32_e32 v56, v57
	v_mov_b32_e32 v57, v58
	v_mul_f32_e32 v92, v96, v136
	v_mov_b32_e32 v96, v97
	v_mov_b32_e32 v97, v98
	v_fma_f32 v59, -v59, v71, v67
; template <int DQK, bool BIAS>
; __device__ __forceinline__ void attn_pass(const hf* __restrict__ Q, int ldq, const hf* __restrict__ Kp, int ldk, const hf* __restrict__ VT,
;                                           int s0, int L, int q0, float scale_l2, const float* sBias, f4 (&oacc)[8][4], char* smem) {
;     ...
; #pragma unroll
;   for (int nq = 0; nq < 4; ++nq) {
;     float lt = lrun[nq]; lt += shx(lt, 16); lt += shx(lt, 32);
;     const float inv = 1.f / lt;
; #pragma unroll
;     for (int md = 0; md < 8; ++md) { oacc[md][nq][0] *= inv; oacc[md][nq][1] *= inv; oacc[md][nq][2] *= inv; oacc[md][nq][3] *= inv; }
;   }
	v_accvgpr_read_b32 v81, a119
	v_accvgpr_read_b32 v99, a103
	v_accvgpr_read_b32 v104, a84
	v_accvgpr_read_b32 v171, a31
	v_accvgpr_read_b32 v122, a14
	v_accvgpr_read_b32 v121, a13
	v_accvgpr_read_b32 v128, a52
	v_accvgpr_read_b32 v154, a4
	v_mul_f32_e32 v156, v113, v136
	v_pk_mul_f32 v[72:73], v[64:65], v[136:137] op_sel_hi:[1,0]
	v_pk_mul_f32 v[64:65], v[56:57], v[136:137] op_sel_hi:[1,0]
	v_mov_b32_e32 v56, v105
	v_mov_b32_e32 v57, v106
	v_pk_mul_f32 v[112:113], v[96:97], v[136:137] op_sel_hi:[1,0]
	v_mul_f32_e32 v96, v78, v136
	v_mov_b32_e32 v78, v79
	v_mov_b32_e32 v79, v80
	v_div_fmas_f32 v59, v59, v63, v71
	v_accvgpr_read_b32 v44, a72
	v_accvgpr_read_b32 v48, a56
	v_accvgpr_read_b32 v135, a43
	v_accvgpr_read_b32 v170, a30
	v_accvgpr_read_b32 v169, a29
	v_mul_f32_e32 v124, v154, v136
	v_mul_f32_e32 v164, v157, v136
	v_mul_f32_e32 v148, v93, v136
	v_mul_f32_e32 v74, v128, v136
	v_mul_f32_e32 v143, v131, v136
	v_mul_f32_e32 v58, v104, v136
	v_pk_mul_f32 v[56:57], v[56:57], v[136:137] op_sel_hi:[1,0]
	v_mul_f32_e32 v157, v107, v136
	v_mul_f32_e32 v158, v99, v136
	v_pk_mul_f32 v[98:99], v[78:79], v[136:137] op_sel_hi:[1,0]
	v_mul_f32_e32 v150, v81, v136
	v_div_fixup_f32 v136, v59, v55, 1.0
	v_mov_b32_e32 v78, v121
	v_mov_b32_e32 v79, v122
	v_accvgpr_read_b32 v45, a73
	v_accvgpr_read_b32 v46, a74
	v_accvgpr_read_b32 v49, a57
	v_accvgpr_read_b32 v50, a58
	v_accvgpr_read_b32 v134, a42
	v_accvgpr_read_b32 v133, a41
	v_accvgpr_read_b32 v120, a12
	v_pk_mul_f32 v[130:131], v[78:79], v[136:137] op_sel_hi:[1,0]
	v_mov_b32_e32 v78, v169
	v_mov_b32_e32 v79, v170
	v_mul_f32_e32 v128, v120, v136
	v_pk_mul_f32 v[120:121], v[78:79], v[136:137] op_sel_hi:[1,0]
	v_mov_b32_e32 v78, v133
	v_mov_b32_e32 v79, v134
	v_mul_f32_e32 v80, v48, v136
	v_mov_b32_e32 v48, v49
	v_mov_b32_e32 v49, v50
	v_mul_f32_e32 v50, v44, v136
	v_mov_b32_e32 v44, v45
	v_mov_b32_e32 v45, v46
	v_accvgpr_read_b32 v36, a108
	v_accvgpr_read_b32 v40, a88
	v_pk_mul_f32 v[104:105], v[78:79], v[136:137] op_sel_hi:[1,0]
	v_pk_mul_f32 v[78:79], v[48:49], v[136:137] op_sel_hi:[1,0]
	v_pk_mul_f32 v[48:49], v[44:45], v[136:137] op_sel_hi:[1,0]
	ds_swizzle_b32 v45, v233 offset:swizzle(SWAP,16)
	v_accvgpr_read_b32 v38, a110
	v_accvgpr_read_b32 v43, a91
	v_mul_f32_e32 v162, v43, v136
	v_mov_b32_e32 v43, v38
	v_mov_b32_e32 v38, v224
	v_accvgpr_read_b32 v37, a109
	v_accvgpr_read_b32 v41, a89
	v_accvgpr_read_b32 v42, a90
	v_lshlrev_b32_e32 v38, 2, v38
	v_mul_f32_e32 v44, v40, v136
	v_mov_b32_e32 v40, v41
	v_mov_b32_e32 v41, v42
	v_mov_b32_e32 v42, v37
	s_waitcnt lgkmcnt(0)
	v_add_f32_e32 v37, v233, v45
	v_bitop3_b32 v38, v38, s3, v226 bitop3:0x6c
	ds_bpermute_b32 v45, v38, v37
	v_accvgpr_read_b32 v32, a120
	v_accvgpr_read_b32 v33, a121
	v_mov_b32_e32 v38, v33
	v_accvgpr_read_b32 v34, a122
	s_waitcnt lgkmcnt(0)
	v_add_f32_e32 v33, v37, v45
	v_div_scale_f32 v37, s[16:17], v33, v33, 1.0
	v_rcp_f32_e32 v45, v37
	v_accvgpr_read_b32 v39, a111
	v_mul_f32_e32 v163, v39, v136
	v_mov_b32_e32 v39, v34
	v_fma_f32 v34, -v37, v45, 1.0
	v_accvgpr_read_b32 v35, a123
	v_fmac_f32_e32 v45, v34, v45
	v_div_scale_f32 v34, vcc, 1.0, v33, 1.0
	v_mul_f32_e32 v155, v35, v136
	v_mul_f32_e32 v35, v34, v45
	v_fma_f32 v46, -v37, v35, v34
	v_fmac_f32_e32 v35, v46, v45
	v_fma_f32 v34, -v37, v35, v34
	v_accvgpr_read_b32 v8, a96
	v_accvgpr_read_b32 v12, a80
	v_accvgpr_read_b32 v16, a60
	v_accvgpr_read_b32 v20, a48
	v_accvgpr_read_b32 v24, a32
	v_accvgpr_read_b32 v31, a23
	v_accvgpr_read_b32 v132, a40
	v_div_fmas_f32 v34, v34, v45, v35
	v_accvgpr_read_b32 v4, a112
	v_accvgpr_read_b32 v9, a97
	v_accvgpr_read_b32 v10, a98
	v_accvgpr_read_b32 v13, a81
	v_accvgpr_read_b32 v14, a82
	v_accvgpr_read_b32 v17, a61
	v_accvgpr_read_b32 v18, a62
	v_accvgpr_read_b32 v21, a49
	v_accvgpr_read_b32 v22, a50
	v_accvgpr_read_b32 v25, a33
	v_accvgpr_read_b32 v26, a34
	v_accvgpr_read_b32 v30, a22
	v_accvgpr_read_b32 v29, a21
	v_accvgpr_read_b32 v28, a20
	v_mul_f32_e32 v106, v132, v136
	v_div_fixup_f32 v132, v34, v33, 1.0
	v_accvgpr_read_b32 v0, a124
	v_accvgpr_read_b32 v5, a113
	v_accvgpr_read_b32 v6, a114
	v_accvgpr_read_b32 v47, a75
	v_mul_f32_e32 v34, v28, v132
	v_mov_b32_e32 v28, v29
	v_mov_b32_e32 v29, v30
	v_mul_f32_e32 v30, v24, v132
	v_mov_b32_e32 v24, v25
	v_mov_b32_e32 v25, v26
	v_mul_f32_e32 v26, v20, v132
	v_mov_b32_e32 v20, v21
	v_mov_b32_e32 v21, v22
	v_mul_f32_e32 v22, v16, v132
	v_mov_b32_e32 v16, v17
	v_mov_b32_e32 v17, v18
	v_mul_f32_e32 v18, v12, v132
	v_mov_b32_e32 v12, v13
	v_mov_b32_e32 v13, v14
	v_mul_f32_e32 v14, v8, v132
	v_mov_b32_e32 v8, v9
	v_mov_b32_e32 v9, v10
	v_accvgpr_read_b32 v1, a125
	v_accvgpr_read_b32 v2, a126
	v_accvgpr_read_b32 v3, a127
	v_accvgpr_read_b32 v7, a115
	v_accvgpr_read_b32 v11, a99
	v_accvgpr_read_b32 v15, a83
	v_accvgpr_read_b32 v19, a63
	v_accvgpr_read_b32 v23, a51
	v_accvgpr_read_b32 v27, a35
	v_accvgpr_read_b32 v51, a59
	v_accvgpr_read_b32 v168, a28
	v_mul_f32_e32 v142, v47, v136
	v_pk_mul_f32 v[46:47], v[28:29], v[132:133] op_sel_hi:[1,0]
	v_pk_mul_f32 v[28:29], v[24:25], v[132:133] op_sel_hi:[1,0]
	v_pk_mul_f32 v[24:25], v[20:21], v[132:133] op_sel_hi:[1,0]
	v_pk_mul_f32 v[20:21], v[16:17], v[132:133] op_sel_hi:[1,0]
	v_pk_mul_f32 v[16:17], v[12:13], v[132:133] op_sel_hi:[1,0]
	v_pk_mul_f32 v[12:13], v[8:9], v[132:133] op_sel_hi:[1,0]
	v_mul_f32_e32 v8, v4, v132
	v_mov_b32_e32 v4, v5
	v_mov_b32_e32 v5, v6
	v_mul_f32_e32 v166, v123, v136
	v_mul_f32_e32 v122, v168, v136
	v_mul_f32_e32 v161, v171, v136
	v_mul_f32_e32 v154, v135, v136
	v_mul_f32_e32 v146, v51, v136
	v_pk_mul_f32 v[40:41], v[40:41], v[136:137] op_sel_hi:[1,0]
	v_mul_f32_e32 v36, v36, v136
	v_pk_mul_f32 v[42:43], v[42:43], v[136:137] op_sel_hi:[1,0]
	v_mul_f32_e32 v32, v32, v136
	v_pk_mul_f32 v[38:39], v[38:39], v[136:137] op_sel_hi:[1,0]
	v_mul_f32_e32 v167, v31, v132
	v_mul_f32_e32 v165, v27, v132
	v_mul_f32_e32 v159, v23, v132
	v_mul_f32_e32 v149, v19, v132
	v_mul_f32_e32 v144, v15, v132
	v_mul_f32_e32 v140, v11, v132
	v_pk_mul_f32 v[4:5], v[4:5], v[132:133] op_sel_hi:[1,0]
	v_mul_f32_e32 v137, v7, v132
	v_pk_mul_f32 v[0:1], v[0:1], v[132:133] op_sel_hi:[1,0]
	s_andn2_b64 vcc, exec, s[62:63]
	v_pk_mul_f32 v[2:3], v[2:3], v[132:133] op_sel_hi:[1,0]
	s_cbranch_vccnz .LBB0_1980
; __device__ __forceinline__ void attn_phase(const Params& p, char* smem, int coff) {
;     ...
; #pragma unroll
;         for (int nq = 0; nq < 4; ++nq) {
;           hf* dst = mix + (size_t)(s0 + q0 + wv * 64 + nq * 16 + fr) * 2048 + 1024 + h * 128 + fq * 4;
;           float ss = 0.f;
; #pragma unroll
;           for (int md = 0; md < 8; ++md) {
;             h4 o0 = *(const h4*)(dst + md * 16);
; #pragma unroll
;             for (int j = 0; j < 4; ++j) { float o = (float)o0[j] - lam * oacc[md][nq][j]; oacc[md][nq][j] = o; ss += o * o; }
;           }
;           ss += shx(ss, 16); ss += shx(ss, 32);
;           const float r = rsqrtf(ss * (1.f / 128.f) + 1e-5f) * (1.f - 0.35550906759f);
	v_accvgpr_read_b32 v247, a225
	v_accvgpr_read_b32 v246, a224
	global_load_dwordx2 v[6:7], v[246:247], off offset:2272
	global_load_dwordx2 v[10:11], v[246:247], off offset:2048
	global_load_dwordx2 v[168:169], v[246:247], off offset:2080
	global_load_dwordx2 v[170:171], v[246:247], off offset:2112
	global_load_dwordx2 v[172:173], v[246:247], off offset:2144
	global_load_dwordx2 v[174:175], v[246:247], off offset:2176
	global_load_dwordx2 v[176:177], v[246:247], off offset:2208
	global_load_dwordx2 v[178:179], v[246:247], off offset:2240
	v_mov_b32_e32 v9, v224
	global_load_dwordx4 v[132:135], v[200:201], off
	v_pk_mov_b32 v[182:183], v[118:119], v[118:119] op_sel:[1,0]
	v_pk_mov_b32 v[180:181], v[88:89], v[88:89] op_sel:[1,0]
	v_mov_b32_e32 v117, v183
	v_mov_b32_e32 v87, v181
	v_mov_b32_e32 v181, v147
	v_mov_b32_e32 v183, v160
	v_pk_mov_b32 v[184:185], v[100:101], v[100:101] op_sel:[1,0]
	v_pk_mov_b32 v[186:187], v[76:77], v[76:77] op_sel:[1,0]
	v_mov_b32_e32 v109, v185
	v_mov_b32_e32 v185, v151
	v_mov_b32_e32 v85, v187
	v_mov_b32_e32 v187, v145
	v_pk_mov_b32 v[188:189], v[68:69], v[68:69] op_sel:[1,0]
	v_pk_mov_b32 v[190:191], v[60:61], v[60:61] op_sel:[1,0]
	v_mov_b32_e32 v71, v189
	v_mov_b32_e32 v189, v141
	v_mov_b32_e32 v63, v191
	v_mov_b32_e32 v191, v138
	v_pk_mov_b32 v[194:195], v[52:53], v[52:53] op_sel:[1,0]
	v_pk_mov_b32 v[242:243], v[102:103], v[102:103] op_sel:[1,0]
	v_mov_b32_e32 v55, v195
	v_mov_b32_e32 v195, v152
	v_mov_b32_e32 v83, v243
	v_mov_b32_e32 v243, v153
	v_lshlrev_b32_e32 v9, 2, v9
	v_bitop3_b32 v9, v9, s3, v226 bitop3:0x6c
	v_accvgpr_read_b32 v249, a227
	v_accvgpr_read_b32 v248, a226
	s_waitcnt vmcnt(8)
	v_cvt_f32_f16_sdwa v205, v7 dst_sel:DWORD dst_unused:UNUSED_PAD src0_sel:WORD_1
	s_waitcnt vmcnt(7)
	v_cvt_f32_f16_sdwa v211, v10 dst_sel:DWORD dst_unused:UNUSED_PAD src0_sel:WORD_1
	v_cvt_f32_f16_e32 v210, v10
	v_cvt_f32_f16_e32 v204, v7
	v_cvt_f32_f16_sdwa v213, v11 dst_sel:DWORD dst_unused:UNUSED_PAD src0_sel:WORD_1
	v_cvt_f32_f16_e32 v212, v11
	s_waitcnt vmcnt(6)
	v_cvt_f32_f16_sdwa v215, v168 dst_sel:DWORD dst_unused:UNUSED_PAD src0_sel:WORD_1
	v_cvt_f32_f16_e32 v214, v168
	v_cvt_f32_f16_sdwa v217, v169 dst_sel:DWORD dst_unused:UNUSED_PAD src0_sel:WORD_1
	v_cvt_f32_f16_e32 v216, v169
	s_waitcnt vmcnt(5)
	v_cvt_f32_f16_sdwa v169, v170 dst_sel:DWORD dst_unused:UNUSED_PAD src0_sel:WORD_1
	v_cvt_f32_f16_e32 v168, v170
	v_cvt_f32_f16_sdwa v219, v171 dst_sel:DWORD dst_unused:UNUSED_PAD src0_sel:WORD_1
	v_cvt_f32_f16_e32 v218, v171
	s_waitcnt vmcnt(4)
	v_cvt_f32_f16_sdwa v171, v172 dst_sel:DWORD dst_unused:UNUSED_PAD src0_sel:WORD_1
	v_cvt_f32_f16_e32 v170, v172
	v_cvt_f32_f16_sdwa v221, v173 dst_sel:DWORD dst_unused:UNUSED_PAD src0_sel:WORD_1
	v_cvt_f32_f16_e32 v220, v173
	s_waitcnt vmcnt(3)
	v_cvt_f32_f16_sdwa v173, v174 dst_sel:DWORD dst_unused:UNUSED_PAD src0_sel:WORD_1
	v_cvt_f32_f16_e32 v172, v174
	v_cvt_f32_f16_sdwa v229, v175 dst_sel:DWORD dst_unused:UNUSED_PAD src0_sel:WORD_1
	v_cvt_f32_f16_e32 v228, v175
	s_waitcnt vmcnt(2)
	v_cvt_f32_f16_sdwa v175, v176 dst_sel:DWORD dst_unused:UNUSED_PAD src0_sel:WORD_1
	v_cvt_f32_f16_e32 v174, v176
	v_cvt_f32_f16_sdwa v231, v177 dst_sel:DWORD dst_unused:UNUSED_PAD src0_sel:WORD_1
	v_cvt_f32_f16_e32 v230, v177
	v_pk_fma_f32 v[176:177], v[192:193], v[116:117], v[210:211] neg_lo:[1,0,0] neg_hi:[1,0,0]
	v_pk_fma_f32 v[10:11], v[192:193], v[180:181], v[204:205] neg_lo:[1,0,0] neg_hi:[1,0,0]
	v_pk_fma_f32 v[180:181], v[192:193], v[182:183], v[212:213] neg_lo:[1,0,0] neg_hi:[1,0,0]
	v_pk_mul_f32 v[210:211], v[176:177], v[176:177]
	v_pk_mul_f32 v[212:213], v[180:181], v[180:181]
	v_add_f32_e32 v15, v210, v211
	v_pk_fma_f32 v[182:183], v[192:193], v[108:109], v[214:215] neg_lo:[1,0,0] neg_hi:[1,0,0]
	v_add_f32_e32 v15, v212, v15
	v_pk_mul_f32 v[214:215], v[182:183], v[182:183]
	v_add_f32_e32 v15, v213, v15
	v_pk_fma_f32 v[184:185], v[192:193], v[184:185], v[216:217] neg_lo:[1,0,0] neg_hi:[1,0,0]
	v_add_f32_e32 v15, v214, v15
	v_pk_mul_f32 v[216:217], v[184:185], v[184:185]
	v_add_f32_e32 v15, v215, v15
	v_pk_fma_f32 v[168:169], v[192:193], v[84:85], v[168:169] neg_lo:[1,0,0] neg_hi:[1,0,0]
	v_add_f32_e32 v15, v216, v15
	v_pk_fma_f32 v[186:187], v[192:193], v[186:187], v[218:219] neg_lo:[1,0,0] neg_hi:[1,0,0]
	v_pk_mul_f32 v[218:219], v[168:169], v[168:169]
	v_add_f32_e32 v15, v217, v15
	v_add_f32_e32 v15, v218, v15
	v_pk_fma_f32 v[188:189], v[192:193], v[188:189], v[220:221] neg_lo:[1,0,0] neg_hi:[1,0,0]
	v_pk_mul_f32 v[220:221], v[186:187], v[186:187]
	v_add_f32_e32 v15, v219, v15
	v_pk_fma_f32 v[170:171], v[192:193], v[70:71], v[170:171] neg_lo:[1,0,0] neg_hi:[1,0,0]
	v_add_f32_e32 v15, v220, v15
	v_pk_fma_f32 v[190:191], v[192:193], v[190:191], v[228:229] neg_lo:[1,0,0] neg_hi:[1,0,0]
	v_pk_mul_f32 v[228:229], v[170:171], v[170:171]
	v_add_f32_e32 v15, v221, v15
	v_add_f32_e32 v15, v228, v15
	v_pk_mul_f32 v[232:233], v[188:189], v[188:189]
	v_add_f32_e32 v15, v229, v15
	v_pk_fma_f32 v[172:173], v[192:193], v[62:63], v[172:173] neg_lo:[1,0,0] neg_hi:[1,0,0]
	v_add_f32_e32 v15, v232, v15
	v_pk_mul_f32 v[234:235], v[172:173], v[172:173]
	v_add_f32_e32 v15, v233, v15
	v_add_f32_e32 v15, v234, v15
	v_pk_mul_f32 v[236:237], v[190:191], v[190:191]
	v_add_f32_e32 v15, v235, v15
	v_pk_fma_f32 v[174:175], v[192:193], v[54:55], v[174:175] neg_lo:[1,0,0] neg_hi:[1,0,0]
	s_waitcnt vmcnt(1)
; __device__ __forceinline__ void attn_phase(const Params& p, char* smem, int coff) {
;     ...
;           float ss = 0.f;
; #pragma unroll
;           for (int md = 0; md < 8; ++md) {
;             h4 o0 = *(const h4*)(dst + md * 16);
; #pragma unroll
;             for (int j = 0; j < 4; ++j) { float o = (float)o0[j] - lam * oacc[md][nq][j]; oacc[md][nq][j] = o; ss += o * o; }
;           }
;           ss += shx(ss, 16); ss += shx(ss, 32);
;           const float r = rsqrtf(ss * (1.f / 128.f) + 1e-5f) * (1.f - 0.35550906759f);
; #pragma unroll
;           for (int md = 0; md < 8; ++md) {
;             f4 gg = *(const f4*)(p.in[41] + md * 16 + fq * 4); h4 o;
; #pragma unroll
;             for (int j = 0; j < 4; ++j) o[j] = (hf)(oacc[md][nq][j] * r * gg[j]);
;             *(h4*)(dst + md * 16) = o;
	v_cvt_f32_f16_sdwa v241, v178 dst_sel:DWORD dst_unused:UNUSED_PAD src0_sel:WORD_1
	v_cvt_f32_f16_e32 v240, v178
	v_add_f32_e32 v15, v236, v15
	v_pk_mul_f32 v[238:239], v[174:175], v[174:175]
	v_add_f32_e32 v15, v237, v15
	v_pk_fma_f32 v[194:195], v[192:193], v[194:195], v[230:231] neg_lo:[1,0,0] neg_hi:[1,0,0]
	v_cvt_f32_f16_sdwa v245, v179 dst_sel:DWORD dst_unused:UNUSED_PAD src0_sel:WORD_1
	v_cvt_f32_f16_e32 v244, v179
	v_add_f32_e32 v15, v238, v15
	v_pk_mul_f32 v[230:231], v[194:195], v[194:195]
	v_add_f32_e32 v15, v239, v15
	v_cvt_f32_f16_sdwa v203, v6 dst_sel:DWORD dst_unused:UNUSED_PAD src0_sel:WORD_1
	v_cvt_f32_f16_e32 v202, v6
	v_pk_fma_f32 v[178:179], v[192:193], v[82:83], v[240:241] neg_lo:[1,0,0] neg_hi:[1,0,0]
	v_add_f32_e32 v15, v230, v15
	v_pk_mul_f32 v[240:241], v[178:179], v[178:179]
	v_add_f32_e32 v15, v231, v15
	v_pk_fma_f32 v[242:243], v[192:193], v[242:243], v[244:245] neg_lo:[1,0,0] neg_hi:[1,0,0]
	v_add_f32_e32 v15, v240, v15
	v_pk_mul_f32 v[244:245], v[242:243], v[242:243]
	v_add_f32_e32 v15, v241, v15
	v_pk_fma_f32 v[6:7], v[192:193], v[86:87], v[202:203] neg_lo:[1,0,0] neg_hi:[1,0,0]
	v_add_f32_e32 v15, v244, v15
	v_pk_mul_f32 v[202:203], v[6:7], v[6:7]
	v_add_f32_e32 v15, v245, v15
	v_add_f32_e32 v15, v202, v15
	v_pk_mul_f32 v[204:205], v[10:11], v[10:11]
	v_add_f32_e32 v15, v203, v15
	v_add_f32_e32 v15, v204, v15
	v_add_f32_e32 v15, v205, v15
	ds_swizzle_b32 v19, v15 offset:swizzle(SWAP,16)
	v_mov_b32_e32 v55, 0x3727c5ac
	v_pk_mov_b32 v[204:205], v[64:65], v[64:65] op_sel:[1,0]
	v_pk_mov_b32 v[212:213], v[112:113], v[112:113] op_sel:[1,0]
	v_mov_b32_e32 v67, v205
	s_waitcnt lgkmcnt(0)
	v_add_f32_e32 v15, v15, v19
	ds_bpermute_b32 v9, v9, v15
	v_mov_b32_e32 v205, v139
	v_mov_b32_e32 v93, v213
	v_mov_b32_e32 v213, v158
	v_pk_mov_b32 v[202:203], v[72:73], v[72:73] op_sel:[1,0]
	s_waitcnt lgkmcnt(0)
	v_add_f32_e32 v9, v15, v9
	v_fmamk_f32 v9, v9, 0x3c000000, v55
	v_mul_f32_e32 v15, 0x4b800000, v9
	v_cmp_gt_f32_e32 vcc, s83, v9
	v_mov_b32_e32 v75, v203
	v_mov_b32_e32 v203, v143
	v_cndmask_b32_e32 v9, v9, v15, vcc
	v_rsq_f32_e32 v9, v9
	v_pk_mov_b32 v[210:211], v[56:57], v[56:57] op_sel:[1,0]
	v_mul_f32_e32 v15, 0x45800000, v9
	v_cndmask_b32_e32 v9, v9, v15, vcc
	v_mul_f32_e32 v136, 0x3f24fd5c, v9
	v_pk_mul_f32 v[176:177], v[176:177], v[136:137] op_sel_hi:[1,0]
	v_pk_mul_f32 v[168:169], v[168:169], v[136:137] op_sel_hi:[1,0]
	s_waitcnt vmcnt(0)
	v_pk_mul_f32 v[132:133], v[132:133], v[176:177]
	v_pk_mul_f32 v[176:177], v[180:181], v[136:137] op_sel_hi:[1,0]
	v_cvt_pk_f16_f32 v132, v132, v133
	v_pk_mul_f32 v[134:135], v[134:135], v[176:177]
	v_pk_mul_f32 v[176:177], v[182:183], v[136:137] op_sel_hi:[1,0]
	v_cvt_pk_f16_f32 v133, v134, v135
	global_store_dwordx2 v[246:247], v[132:133], off offset:2048
	global_load_dwordx4 v[132:135], v[200:201], off offset:64
	v_pk_mul_f32 v[180:181], v[184:185], v[136:137] op_sel_hi:[1,0]
	v_pk_mul_f32 v[6:7], v[6:7], v[136:137] op_sel_hi:[1,0]
	v_pk_mul_f32 v[10:11], v[10:11], v[136:137] op_sel_hi:[1,0]
	v_mov_b32_e32 v9, v224
	v_mov_b32_e32 v59, v211
	v_mov_b32_e32 v211, v157
	s_waitcnt vmcnt(0)
	v_pk_mul_f32 v[132:133], v[132:133], v[176:177]
	v_pk_mul_f32 v[134:135], v[134:135], v[180:181]
	v_cvt_pk_f16_f32 v132, v132, v133
	v_cvt_pk_f16_f32 v133, v134, v135
	global_store_dwordx2 v[246:247], v[132:133], off offset:2080
	global_load_dwordx4 v[132:135], v[200:201], off offset:128
	v_pk_mul_f32 v[176:177], v[186:187], v[136:137] op_sel_hi:[1,0]
	s_waitcnt vmcnt(0)
	v_pk_mul_f32 v[132:133], v[132:133], v[168:169]
	v_pk_mul_f32 v[134:135], v[134:135], v[176:177]
	v_cvt_pk_f16_f32 v132, v132, v133
	v_cvt_pk_f16_f32 v133, v134, v135
	global_store_dwordx2 v[246:247], v[132:133], off offset:2112
	global_load_dwordx4 v[132:135], v[200:201], off offset:192
	v_pk_mul_f32 v[168:169], v[170:171], v[136:137] op_sel_hi:[1,0]
	v_pk_mul_f32 v[170:171], v[188:189], v[136:137] op_sel_hi:[1,0]
	s_waitcnt vmcnt(0)
	v_pk_mul_f32 v[132:133], v[132:133], v[168:169]
	v_pk_mul_f32 v[134:135], v[134:135], v[170:171]
	v_cvt_pk_f16_f32 v132, v132, v133
	v_cvt_pk_f16_f32 v133, v134, v135
	global_store_dwordx2 v[246:247], v[132:133], off offset:2144
	global_load_dwordx4 v[132:135], v[200:201], off offset:256
	v_pk_mul_f32 v[168:169], v[172:173], v[136:137] op_sel_hi:[1,0]
	v_pk_mul_f32 v[170:171], v[190:191], v[136:137] op_sel_hi:[1,0]
	v_pk_mov_b32 v[190:191], v[110:111], v[110:111] op_sel:[1,0]
	s_waitcnt vmcnt(0)
	v_pk_mul_f32 v[132:133], v[132:133], v[168:169]
	v_pk_mul_f32 v[134:135], v[134:135], v[170:171]
	v_cvt_pk_f16_f32 v132, v132, v133
	v_cvt_pk_f16_f32 v133, v134, v135
	global_store_dwordx2 v[246:247], v[132:133], off offset:2176
	global_load_dwordx4 v[132:135], v[200:201], off offset:320
	v_pk_mul_f32 v[168:169], v[174:175], v[136:137] op_sel_hi:[1,0]
	v_pk_mul_f32 v[170:171], v[194:195], v[136:137] op_sel_hi:[1,0]
	v_mov_b32_e32 v115, v191
	v_mov_b32_e32 v191, v156
	v_pk_mov_b32 v[194:195], v[90:91], v[90:91] op_sel:[1,0]
	s_waitcnt vmcnt(0)
	v_pk_mul_f32 v[132:133], v[132:133], v[168:169]
	v_pk_mul_f32 v[134:135], v[134:135], v[170:171]
	v_cvt_pk_f16_f32 v132, v132, v133
	v_cvt_pk_f16_f32 v133, v134, v135
	global_store_dwordx2 v[246:247], v[132:133], off offset:2208
	global_load_dwordx4 v[132:135], v[200:201], off offset:384
	v_pk_mul_f32 v[168:169], v[178:179], v[136:137] op_sel_hi:[1,0]
	v_pk_mul_f32 v[170:171], v[242:243], v[136:137] op_sel_hi:[1,0]
	global_load_dwordx2 v[172:173], v[248:249], off offset:2272
	global_load_dwordx2 v[174:175], v[248:249], off offset:2048
	global_load_dwordx2 v[176:177], v[248:249], off offset:2080
	global_load_dwordx2 v[180:181], v[248:249], off offset:2112
	global_load_dwordx2 v[182:183], v[248:249], off offset:2144
	global_load_dwordx2 v[184:185], v[248:249], off offset:2176
	global_load_dwordx2 v[186:187], v[248:249], off offset:2208
	global_load_dwordx2 v[188:189], v[248:249], off offset:2240
	v_pk_mov_b32 v[178:179], v[126:127], v[126:127] op_sel:[1,0]
	v_mov_b32_e32 v95, v195
	v_mov_b32_e32 v125, v179
	v_mov_b32_e32 v179, v164
	v_mov_b32_e32 v195, v148
	s_waitcnt vmcnt(7)
; __device__ __forceinline__ void attn_phase(const Params& p, char* smem, int coff) {
;     ...
;           float ss = 0.f;
; #pragma unroll
;           for (int md = 0; md < 8; ++md) {
;             h4 o0 = *(const h4*)(dst + md * 16);
; #pragma unroll
;             for (int j = 0; j < 4; ++j) { float o = (float)o0[j] - lam * oacc[md][nq][j]; oacc[md][nq][j] = o; ss += o * o; }
;           }
;           ss += shx(ss, 16); ss += shx(ss, 32);
;           const float r = rsqrtf(ss * (1.f / 128.f) + 1e-5f) * (1.f - 0.35550906759f);
; #pragma unroll
;           for (int md = 0; md < 8; ++md) {
;             f4 gg = *(const f4*)(p.in[41] + md * 16 + fq * 4); h4 o;
; #pragma unroll
;             for (int j = 0; j < 4; ++j) o[j] = (hf)(oacc[md][nq][j] * r * gg[j]);
;             *(h4*)(dst + md * 16) = o;
	v_cvt_f32_f16_sdwa v215, v173 dst_sel:DWORD dst_unused:UNUSED_PAD src0_sel:WORD_1
	v_cvt_f32_f16_e32 v214, v173
	s_waitcnt vmcnt(6)
	v_cvt_f32_f16_sdwa v173, v174 dst_sel:DWORD dst_unused:UNUSED_PAD src0_sel:WORD_1
	v_cvt_f32_f16_sdwa v217, v175 dst_sel:DWORD dst_unused:UNUSED_PAD src0_sel:WORD_1
	v_pk_mul_f32 v[132:133], v[132:133], v[168:169]
	v_pk_mul_f32 v[134:135], v[134:135], v[170:171]
	v_cvt_pk_f16_f32 v132, v132, v133
	v_cvt_pk_f16_f32 v133, v134, v135
	global_store_dwordx2 v[246:247], v[132:133], off offset:2240
	global_load_dwordx4 v[168:171], v[200:201], off offset:448
	v_cvt_f32_f16_sdwa v133, v172 dst_sel:DWORD dst_unused:UNUSED_PAD src0_sel:WORD_1
	v_cvt_f32_f16_e32 v132, v172
	v_cvt_f32_f16_e32 v172, v174
	v_cvt_f32_f16_e32 v216, v175
	s_waitcnt vmcnt(4)
	v_cvt_f32_f16_sdwa v231, v185 dst_sel:DWORD dst_unused:UNUSED_PAD src0_sel:WORD_1
	v_cvt_f32_f16_e32 v230, v185
	s_waitcnt vmcnt(2)
	v_cvt_f32_f16_sdwa v235, v189 dst_sel:DWORD dst_unused:UNUSED_PAD src0_sel:WORD_1
	v_cvt_f32_f16_e32 v234, v189
	v_cvt_f32_f16_sdwa v175, v176 dst_sel:DWORD dst_unused:UNUSED_PAD src0_sel:WORD_1
	v_cvt_f32_f16_e32 v174, v176
	v_pk_mov_b32 v[134:135], v[98:99], v[98:99] op_sel:[1,0]
	v_pk_fma_f32 v[172:173], v[192:193], v[124:125], v[172:173] neg_lo:[1,0,0] neg_hi:[1,0,0]
	v_mov_b32_e32 v97, v135
	v_mov_b32_e32 v135, v150
	v_cvt_f32_f16_sdwa v219, v177 dst_sel:DWORD dst_unused:UNUSED_PAD src0_sel:WORD_1
	v_cvt_f32_f16_e32 v218, v177
	v_pk_fma_f32 v[178:179], v[192:193], v[178:179], v[216:217] neg_lo:[1,0,0] neg_hi:[1,0,0]
	v_pk_fma_f32 v[134:135], v[192:193], v[134:135], v[214:215] neg_lo:[1,0,0] neg_hi:[1,0,0]
	v_pk_mul_f32 v[214:215], v[178:179], v[178:179]
	v_cvt_f32_f16_sdwa v177, v180 dst_sel:DWORD dst_unused:UNUSED_PAD src0_sel:WORD_1
	v_cvt_f32_f16_e32 v176, v180
	v_pk_fma_f32 v[174:175], v[192:193], v[114:115], v[174:175] neg_lo:[1,0,0] neg_hi:[1,0,0]
	v_cvt_f32_f16_sdwa v221, v181 dst_sel:DWORD dst_unused:UNUSED_PAD src0_sel:WORD_1
	v_cvt_f32_f16_e32 v220, v181
	v_pk_mul_f32 v[216:217], v[174:175], v[174:175]
	v_cvt_f32_f16_sdwa v181, v182 dst_sel:DWORD dst_unused:UNUSED_PAD src0_sel:WORD_1
	v_cvt_f32_f16_e32 v180, v182
	v_cvt_f32_f16_sdwa v229, v183 dst_sel:DWORD dst_unused:UNUSED_PAD src0_sel:WORD_1
	v_cvt_f32_f16_e32 v228, v183
	v_cvt_f32_f16_sdwa v183, v184 dst_sel:DWORD dst_unused:UNUSED_PAD src0_sel:WORD_1
	v_cvt_f32_f16_e32 v182, v184
	v_cvt_f32_f16_sdwa v185, v186 dst_sel:DWORD dst_unused:UNUSED_PAD src0_sel:WORD_1
	v_cvt_f32_f16_e32 v184, v186
	v_cvt_f32_f16_sdwa v233, v187 dst_sel:DWORD dst_unused:UNUSED_PAD src0_sel:WORD_1
	v_cvt_f32_f16_e32 v232, v187
	v_cvt_f32_f16_sdwa v187, v188 dst_sel:DWORD dst_unused:UNUSED_PAD src0_sel:WORD_1
	v_cvt_f32_f16_e32 v186, v188
	v_pk_fma_f32 v[188:189], v[192:193], v[190:191], v[218:219] neg_lo:[1,0,0] neg_hi:[1,0,0]
	v_pk_fma_f32 v[176:177], v[192:193], v[94:95], v[176:177] neg_lo:[1,0,0] neg_hi:[1,0,0]
	v_pk_mul_f32 v[218:219], v[188:189], v[188:189]
	v_pk_fma_f32 v[190:191], v[192:193], v[194:195], v[220:221] neg_lo:[1,0,0] neg_hi:[1,0,0]
	v_pk_mul_f32 v[220:221], v[176:177], v[176:177]
	v_pk_fma_f32 v[194:195], v[192:193], v[202:203], v[228:229] neg_lo:[1,0,0] neg_hi:[1,0,0]
	v_pk_mul_f32 v[228:229], v[190:191], v[190:191]
	v_pk_fma_f32 v[180:181], v[192:193], v[74:75], v[180:181] neg_lo:[1,0,0] neg_hi:[1,0,0]
	v_pk_fma_f32 v[202:203], v[192:193], v[210:211], v[232:233] neg_lo:[1,0,0] neg_hi:[1,0,0]
	v_pk_mul_f32 v[232:233], v[194:195], v[194:195]
	v_pk_fma_f32 v[182:183], v[192:193], v[66:67], v[182:183] neg_lo:[1,0,0] neg_hi:[1,0,0]
	v_pk_fma_f32 v[184:185], v[192:193], v[58:59], v[184:185] neg_lo:[1,0,0] neg_hi:[1,0,0]
	v_pk_mul_f32 v[240:241], v[202:203], v[202:203]
	v_pk_mul_f32 v[238:239], v[184:185], v[184:185]
	v_pk_fma_f32 v[186:187], v[192:193], v[92:93], v[186:187] neg_lo:[1,0,0] neg_hi:[1,0,0]
	v_pk_fma_f32 v[132:133], v[192:193], v[96:97], v[132:133] neg_lo:[1,0,0] neg_hi:[1,0,0]
	v_pk_mul_f32 v[242:243], v[186:187], v[186:187]
	v_pk_mul_f32 v[210:211], v[134:135], v[134:135]
	s_waitcnt vmcnt(0)
	v_pk_mul_f32 v[6:7], v[168:169], v[6:7]
	v_pk_mul_f32 v[10:11], v[170:171], v[10:11]
	v_cvt_pk_f16_f32 v6, v6, v7
	v_cvt_pk_f16_f32 v7, v10, v11
	global_store_dwordx2 v[246:247], v[6:7], off offset:2272
	global_load_dwordx4 v[168:171], v[200:201], off
	v_pk_fma_f32 v[10:11], v[192:193], v[204:205], v[230:231] neg_lo:[1,0,0] neg_hi:[1,0,0]
	v_pk_fma_f32 v[204:205], v[192:193], v[212:213], v[234:235] neg_lo:[1,0,0] neg_hi:[1,0,0]
	v_pk_mul_f32 v[212:213], v[172:173], v[172:173]
	v_pk_mul_f32 v[230:231], v[180:181], v[180:181]
	v_add_f32_e32 v15, v212, v213
	v_add_f32_e32 v15, v214, v15
	v_add_f32_e32 v15, v215, v15
	v_add_f32_e32 v15, v216, v15
	v_add_f32_e32 v15, v217, v15
	v_add_f32_e32 v15, v218, v15
	v_add_f32_e32 v15, v219, v15
	v_add_f32_e32 v15, v220, v15
	v_add_f32_e32 v15, v221, v15
	v_add_f32_e32 v15, v228, v15
	v_add_f32_e32 v15, v229, v15
	v_add_f32_e32 v15, v230, v15
	v_add_f32_e32 v15, v231, v15
	v_add_f32_e32 v15, v232, v15
	v_pk_mul_f32 v[234:235], v[182:183], v[182:183]
	v_add_f32_e32 v15, v233, v15
	v_add_f32_e32 v15, v234, v15
	v_pk_mul_f32 v[236:237], v[10:11], v[10:11]
	v_add_f32_e32 v15, v235, v15
	v_add_f32_e32 v15, v236, v15
	v_add_f32_e32 v15, v237, v15
	v_add_f32_e32 v15, v238, v15
	v_add_f32_e32 v15, v239, v15
	v_add_f32_e32 v15, v240, v15
	v_add_f32_e32 v15, v241, v15
	v_add_f32_e32 v15, v242, v15
	v_pk_mul_f32 v[244:245], v[204:205], v[204:205]
	v_add_f32_e32 v15, v243, v15
	v_add_f32_e32 v15, v244, v15
	v_pk_mul_f32 v[6:7], v[132:133], v[132:133]
	v_add_f32_e32 v15, v245, v15
	v_add_f32_e32 v6, v6, v15
	v_add_f32_e32 v6, v7, v6
	v_add_f32_e32 v6, v210, v6
	v_add_f32_e32 v6, v211, v6
	ds_swizzle_b32 v7, v6 offset:swizzle(SWAP,16)
	v_pk_mov_b32 v[212:213], v[42:43], v[42:43] op_sel:[1,0]
	v_pk_mov_b32 v[210:211], v[40:41], v[40:41] op_sel:[1,0]
	v_mov_b32_e32 v37, v213
	v_mov_b32_e32 v213, v163
	s_waitcnt lgkmcnt(0)
; __device__ __forceinline__ void attn_phase(const Params& p, char* smem, int coff) {
;     ...
;           float ss = 0.f;
; #pragma unroll
;           for (int md = 0; md < 8; ++md) {
;             h4 o0 = *(const h4*)(dst + md * 16);
; #pragma unroll
;             for (int j = 0; j < 4; ++j) { float o = (float)o0[j] - lam * oacc[md][nq][j]; oacc[md][nq][j] = o; ss += o * o; }
;           }
;           ss += shx(ss, 16); ss += shx(ss, 32);
;           const float r = rsqrtf(ss * (1.f / 128.f) + 1e-5f) * (1.f - 0.35550906759f);
; #pragma unroll
;           for (int md = 0; md < 8; ++md) {
;             f4 gg = *(const f4*)(p.in[41] + md * 16 + fq * 4); h4 o;
; #pragma unroll
;             for (int j = 0; j < 4; ++j) o[j] = (hf)(oacc[md][nq][j] * r * gg[j]);
;             *(h4*)(dst + md * 16) = o;
	v_add_f32_e32 v6, v6, v7
	v_lshlrev_b32_e32 v7, 2, v9
	v_bitop3_b32 v7, v7, s3, v226 bitop3:0x6c
	ds_bpermute_b32 v7, v7, v6
	v_mov_b32_e32 v9, v224
	v_mov_b32_e32 v45, v211
	v_mov_b32_e32 v211, v162
	s_waitcnt lgkmcnt(0)
	v_add_f32_e32 v6, v6, v7
	v_fmamk_f32 v6, v6, 0x3c000000, v55
	v_mul_f32_e32 v7, 0x4b800000, v6
	v_cmp_gt_f32_e32 vcc, s83, v6
	s_nop 1
	v_cndmask_b32_e32 v6, v6, v7, vcc
	v_rsq_f32_e32 v6, v6
	s_nop 0
	v_mul_f32_e32 v7, 0x45800000, v6
	v_cndmask_b32_e32 v6, v6, v7, vcc
	v_mul_f32_e32 v6, 0x3f24fd5c, v6
	v_pk_mul_f32 v[172:173], v[172:173], v[6:7] op_sel_hi:[1,0]
	v_pk_mul_f32 v[178:179], v[178:179], v[6:7] op_sel_hi:[1,0]
	v_pk_mul_f32 v[10:11], v[10:11], v[6:7] op_sel_hi:[1,0]
	v_pk_mul_f32 v[186:187], v[186:187], v[6:7] op_sel_hi:[1,0]
	v_pk_mul_f32 v[132:133], v[132:133], v[6:7] op_sel_hi:[1,0]
	v_pk_mul_f32 v[134:135], v[134:135], v[6:7] op_sel_hi:[1,0]
	s_waitcnt vmcnt(0)
	v_pk_mul_f32 v[168:169], v[168:169], v[172:173]
	v_pk_mul_f32 v[170:171], v[170:171], v[178:179]
	v_cvt_pk_f16_f32 v168, v168, v169
	v_cvt_pk_f16_f32 v169, v170, v171
	global_store_dwordx2 v[248:249], v[168:169], off offset:2048
	global_load_dwordx4 v[168:171], v[200:201], off offset:64
	v_pk_mul_f32 v[172:173], v[174:175], v[6:7] op_sel_hi:[1,0]
	v_pk_mul_f32 v[174:175], v[188:189], v[6:7] op_sel_hi:[1,0]
	v_pk_mul_f32 v[188:189], v[204:205], v[6:7] op_sel_hi:[1,0]
	v_pk_mov_b32 v[204:205], v[48:49], v[48:49] op_sel:[1,0]
	s_waitcnt vmcnt(0)
	v_pk_mul_f32 v[168:169], v[168:169], v[172:173]
	v_pk_mul_f32 v[170:171], v[170:171], v[174:175]
	v_cvt_pk_f16_f32 v168, v168, v169
	v_cvt_pk_f16_f32 v169, v170, v171
	global_store_dwordx2 v[248:249], v[168:169], off offset:2080
	global_load_dwordx4 v[168:171], v[200:201], off offset:128
	v_pk_mul_f32 v[172:173], v[176:177], v[6:7] op_sel_hi:[1,0]
	v_pk_mul_f32 v[174:175], v[190:191], v[6:7] op_sel_hi:[1,0]
	v_mov_b32_e32 v51, v205
	v_mov_b32_e32 v205, v142
	v_pk_mov_b32 v[190:191], v[120:121], v[120:121] op_sel:[1,0]
	s_waitcnt vmcnt(0)
	v_pk_mul_f32 v[168:169], v[168:169], v[172:173]
	v_pk_mul_f32 v[170:171], v[170:171], v[174:175]
	v_cvt_pk_f16_f32 v168, v168, v169
	v_cvt_pk_f16_f32 v169, v170, v171
	global_store_dwordx2 v[248:249], v[168:169], off offset:2112
	global_load_dwordx4 v[168:171], v[200:201], off offset:192
	v_pk_mul_f32 v[172:173], v[180:181], v[6:7] op_sel_hi:[1,0]
	v_pk_mul_f32 v[174:175], v[194:195], v[6:7] op_sel_hi:[1,0]
	v_mov_b32_e32 v123, v191
	v_mov_b32_e32 v191, v161
	v_pk_mov_b32 v[194:195], v[104:105], v[104:105] op_sel:[1,0]
	s_waitcnt vmcnt(0)
	v_pk_mul_f32 v[168:169], v[168:169], v[172:173]
	v_pk_mul_f32 v[170:171], v[170:171], v[174:175]
	v_cvt_pk_f16_f32 v168, v168, v169
	v_cvt_pk_f16_f32 v169, v170, v171
	global_store_dwordx2 v[248:249], v[168:169], off offset:2144
	global_load_dwordx4 v[168:171], v[200:201], off offset:256
	v_pk_mul_f32 v[172:173], v[182:183], v[6:7] op_sel_hi:[1,0]
	v_mov_b32_e32 v107, v195
	v_mov_b32_e32 v195, v154
	s_waitcnt vmcnt(0)
	v_pk_mul_f32 v[168:169], v[168:169], v[172:173]
	v_pk_mul_f32 v[10:11], v[170:171], v[10:11]
	v_cvt_pk_f16_f32 v168, v168, v169
	v_cvt_pk_f16_f32 v169, v10, v11
	global_store_dwordx2 v[248:249], v[168:169], off offset:2176
	global_load_dwordx4 v[168:171], v[200:201], off offset:320
	v_pk_mul_f32 v[10:11], v[184:185], v[6:7] op_sel_hi:[1,0]
	v_pk_mul_f32 v[172:173], v[202:203], v[6:7] op_sel_hi:[1,0]
	v_pk_mov_b32 v[202:203], v[78:79], v[78:79] op_sel:[1,0]
	s_waitcnt vmcnt(0)
	v_pk_mul_f32 v[10:11], v[168:169], v[10:11]
	v_pk_mul_f32 v[168:169], v[170:171], v[172:173]
	v_cvt_pk_f16_f32 v10, v10, v11
	v_cvt_pk_f16_f32 v11, v168, v169
	global_store_dwordx2 v[248:249], v[10:11], off offset:2208
	global_load_dwordx4 v[168:171], v[200:201], off offset:384
	s_nop 0
	global_load_dwordx2 v[10:11], v[206:207], off offset:2272
	global_load_dwordx2 v[172:173], v[206:207], off offset:2048
	global_load_dwordx2 v[174:175], v[206:207], off offset:2080
	global_load_dwordx2 v[176:177], v[206:207], off offset:2112
	global_load_dwordx2 v[178:179], v[206:207], off offset:2144
	global_load_dwordx2 v[180:181], v[206:207], off offset:2176
	global_load_dwordx2 v[182:183], v[206:207], off offset:2208
	global_load_dwordx2 v[184:185], v[206:207], off offset:2240
	v_mov_b32_e32 v81, v203
	v_mov_b32_e32 v203, v146
	s_waitcnt vmcnt(8)
	v_pk_mul_f32 v[168:169], v[168:169], v[186:187]
	v_pk_mul_f32 v[170:171], v[170:171], v[188:189]
	v_cvt_pk_f16_f32 v168, v168, v169
	v_cvt_pk_f16_f32 v169, v170, v171
	global_store_dwordx2 v[248:249], v[168:169], off offset:2240
	global_load_dwordx4 v[168:171], v[200:201], off offset:448
	s_waitcnt vmcnt(8)
	v_cvt_f32_f16_sdwa v217, v172 dst_sel:DWORD dst_unused:UNUSED_PAD src0_sel:WORD_1
	v_cvt_f32_f16_e32 v216, v172
	v_cvt_f32_f16_sdwa v215, v11 dst_sel:DWORD dst_unused:UNUSED_PAD src0_sel:WORD_1
	v_cvt_f32_f16_e32 v214, v11
	v_cvt_f32_f16_sdwa v219, v173 dst_sel:DWORD dst_unused:UNUSED_PAD src0_sel:WORD_1
	v_cvt_f32_f16_e32 v218, v173
	s_waitcnt vmcnt(4)
	v_cvt_f32_f16_sdwa v233, v181 dst_sel:DWORD dst_unused:UNUSED_PAD src0_sel:WORD_1
	v_cvt_f32_f16_e32 v232, v181
	s_waitcnt vmcnt(2)
; __device__ __forceinline__ void attn_phase(const Params& p, char* smem, int coff) {
;     ...
;           float ss = 0.f;
; #pragma unroll
;           for (int md = 0; md < 8; ++md) {
;             h4 o0 = *(const h4*)(dst + md * 16);
; #pragma unroll
;             for (int j = 0; j < 4; ++j) { float o = (float)o0[j] - lam * oacc[md][nq][j]; oacc[md][nq][j] = o; ss += o * o; }
;           }
;           ss += shx(ss, 16); ss += shx(ss, 32);
;           const float r = rsqrtf(ss * (1.f / 128.f) + 1e-5f) * (1.f - 0.35550906759f);
; #pragma unroll
;           for (int md = 0; md < 8; ++md) {
;             f4 gg = *(const f4*)(p.in[41] + md * 16 + fq * 4); h4 o;
; #pragma unroll
;             for (int j = 0; j < 4; ++j) o[j] = (hf)(oacc[md][nq][j] * r * gg[j]);
;             *(h4*)(dst + md * 16) = o;
	v_cvt_f32_f16_sdwa v237, v185 dst_sel:DWORD dst_unused:UNUSED_PAD src0_sel:WORD_1
	v_cvt_f32_f16_e32 v236, v185
	v_pk_mov_b32 v[188:189], v[130:131], v[130:131] op_sel:[1,0]
	v_pk_mov_b32 v[186:187], v[38:39], v[38:39] op_sel:[1,0]
	v_mov_b32_e32 v129, v189
	v_cvt_f32_f16_sdwa v173, v174 dst_sel:DWORD dst_unused:UNUSED_PAD src0_sel:WORD_1
	v_cvt_f32_f16_e32 v172, v174
	v_mov_b32_e32 v33, v187
	v_mov_b32_e32 v187, v155
	v_mov_b32_e32 v189, v166
	v_cvt_f32_f16_sdwa v221, v175 dst_sel:DWORD dst_unused:UNUSED_PAD src0_sel:WORD_1
	v_cvt_f32_f16_e32 v220, v175
	v_cvt_f32_f16_sdwa v175, v176 dst_sel:DWORD dst_unused:UNUSED_PAD src0_sel:WORD_1
	v_cvt_f32_f16_e32 v174, v176
	v_cvt_f32_f16_sdwa v229, v177 dst_sel:DWORD dst_unused:UNUSED_PAD src0_sel:WORD_1
	v_cvt_f32_f16_e32 v228, v177
	v_cvt_f32_f16_sdwa v177, v178 dst_sel:DWORD dst_unused:UNUSED_PAD src0_sel:WORD_1
	v_cvt_f32_f16_e32 v176, v178
	v_cvt_f32_f16_sdwa v231, v179 dst_sel:DWORD dst_unused:UNUSED_PAD src0_sel:WORD_1
	v_cvt_f32_f16_e32 v230, v179
	v_cvt_f32_f16_sdwa v179, v180 dst_sel:DWORD dst_unused:UNUSED_PAD src0_sel:WORD_1
	v_cvt_f32_f16_e32 v178, v180
	v_cvt_f32_f16_sdwa v181, v182 dst_sel:DWORD dst_unused:UNUSED_PAD src0_sel:WORD_1
	v_cvt_f32_f16_e32 v180, v182
	v_cvt_f32_f16_sdwa v235, v183 dst_sel:DWORD dst_unused:UNUSED_PAD src0_sel:WORD_1
	v_cvt_f32_f16_e32 v234, v183
	v_cvt_f32_f16_sdwa v183, v184 dst_sel:DWORD dst_unused:UNUSED_PAD src0_sel:WORD_1
	v_cvt_f32_f16_e32 v182, v184
	v_pk_fma_f32 v[184:185], v[192:193], v[128:129], v[216:217] neg_lo:[1,0,0] neg_hi:[1,0,0]
	v_cvt_f32_f16_sdwa v7, v10 dst_sel:DWORD dst_unused:UNUSED_PAD src0_sel:WORD_1
	v_cvt_f32_f16_e32 v6, v10
	v_pk_fma_f32 v[10:11], v[192:193], v[186:187], v[214:215] neg_lo:[1,0,0] neg_hi:[1,0,0]
	v_pk_fma_f32 v[186:187], v[192:193], v[188:189], v[218:219] neg_lo:[1,0,0] neg_hi:[1,0,0]
	v_pk_fma_f32 v[172:173], v[192:193], v[122:123], v[172:173] neg_lo:[1,0,0] neg_hi:[1,0,0]
	v_pk_mul_f32 v[214:215], v[186:187], v[186:187]
	v_pk_mul_f32 v[216:217], v[172:173], v[172:173]
	v_pk_fma_f32 v[188:189], v[192:193], v[190:191], v[220:221] neg_lo:[1,0,0] neg_hi:[1,0,0]
	v_pk_fma_f32 v[174:175], v[192:193], v[106:107], v[174:175] neg_lo:[1,0,0] neg_hi:[1,0,0]
	v_pk_mul_f32 v[218:219], v[188:189], v[188:189]
	v_pk_mul_f32 v[220:221], v[174:175], v[174:175]
	v_pk_fma_f32 v[190:191], v[192:193], v[194:195], v[228:229] neg_lo:[1,0,0] neg_hi:[1,0,0]
	v_pk_fma_f32 v[176:177], v[192:193], v[80:81], v[176:177] neg_lo:[1,0,0] neg_hi:[1,0,0]
	v_pk_mul_f32 v[228:229], v[190:191], v[190:191]
	v_pk_fma_f32 v[194:195], v[192:193], v[202:203], v[230:231] neg_lo:[1,0,0] neg_hi:[1,0,0]
	v_pk_mul_f32 v[230:231], v[176:177], v[176:177]
	v_pk_fma_f32 v[178:179], v[192:193], v[50:51], v[178:179] neg_lo:[1,0,0] neg_hi:[1,0,0]
	v_pk_fma_f32 v[202:203], v[192:193], v[210:211], v[234:235] neg_lo:[1,0,0] neg_hi:[1,0,0]
	v_pk_mul_f32 v[234:235], v[178:179], v[178:179]
	v_pk_fma_f32 v[180:181], v[192:193], v[44:45], v[180:181] neg_lo:[1,0,0] neg_hi:[1,0,0]
	v_pk_mul_f32 v[240:241], v[202:203], v[202:203]
	v_pk_mul_f32 v[238:239], v[180:181], v[180:181]
	v_pk_fma_f32 v[182:183], v[192:193], v[36:37], v[182:183] neg_lo:[1,0,0] neg_hi:[1,0,0]
	v_pk_fma_f32 v[6:7], v[192:193], v[32:33], v[6:7] neg_lo:[1,0,0] neg_hi:[1,0,0]
	v_pk_mul_f32 v[242:243], v[182:183], v[182:183]
	v_pk_mul_f32 v[210:211], v[10:11], v[10:11]
	v_mov_b32_e32 v33, v224
	s_waitcnt vmcnt(0)
	v_pk_mul_f32 v[132:133], v[168:169], v[132:133]
	v_pk_mul_f32 v[134:135], v[170:171], v[134:135]
	v_cvt_pk_f16_f32 v132, v132, v133
	v_cvt_pk_f16_f32 v133, v134, v135
	global_store_dwordx2 v[248:249], v[132:133], off offset:2272
	global_load_dwordx4 v[168:171], v[200:201], off
	v_pk_fma_f32 v[134:135], v[192:193], v[204:205], v[232:233] neg_lo:[1,0,0] neg_hi:[1,0,0]
	v_pk_fma_f32 v[204:205], v[192:193], v[212:213], v[236:237] neg_lo:[1,0,0] neg_hi:[1,0,0]
	v_pk_mul_f32 v[212:213], v[184:185], v[184:185]
	v_pk_mul_f32 v[232:233], v[194:195], v[194:195]
	v_add_f32_e32 v15, v212, v213
	v_add_f32_e32 v15, v214, v15
	v_add_f32_e32 v15, v215, v15
	v_add_f32_e32 v15, v216, v15
	v_add_f32_e32 v15, v217, v15
	v_add_f32_e32 v15, v218, v15
	v_add_f32_e32 v15, v219, v15
	v_add_f32_e32 v15, v220, v15
	v_add_f32_e32 v15, v221, v15
	v_add_f32_e32 v15, v228, v15
	v_add_f32_e32 v15, v229, v15
	v_add_f32_e32 v15, v230, v15
	v_add_f32_e32 v15, v231, v15
	v_add_f32_e32 v15, v232, v15
	v_add_f32_e32 v15, v233, v15
	v_add_f32_e32 v15, v234, v15
	v_pk_mul_f32 v[236:237], v[134:135], v[134:135]
	v_add_f32_e32 v15, v235, v15
	v_add_f32_e32 v15, v236, v15
	v_add_f32_e32 v15, v237, v15
	v_add_f32_e32 v15, v238, v15
	v_add_f32_e32 v15, v239, v15
	v_add_f32_e32 v15, v240, v15
	v_add_f32_e32 v15, v241, v15
	v_add_f32_e32 v15, v242, v15
	v_pk_mul_f32 v[244:245], v[204:205], v[204:205]
	v_add_f32_e32 v15, v243, v15
	v_add_f32_e32 v15, v244, v15
	v_pk_mul_f32 v[132:133], v[6:7], v[6:7]
	v_add_f32_e32 v15, v245, v15
	v_add_f32_e32 v15, v132, v15
	v_add_f32_e32 v15, v133, v15
	v_add_f32_e32 v15, v210, v15
	v_add_f32_e32 v15, v211, v15
	ds_swizzle_b32 v19, v15 offset:swizzle(SWAP,16)
	v_lshlrev_b32_e32 v9, 2, v9
	v_bitop3_b32 v9, v9, s3, v226 bitop3:0x6c
	v_pk_mov_b32 v[210:211], v[4:5], v[4:5] op_sel:[1,0]
	s_waitcnt lgkmcnt(0)
	v_add_f32_e32 v15, v15, v19
	ds_bpermute_b32 v9, v9, v15
	s_waitcnt lgkmcnt(0)
; __device__ __forceinline__ void attn_phase(const Params& p, char* smem, int coff) {
;     ...
;             h4 o0 = *(const h4*)(dst + md * 16);
; #pragma unroll
;             for (int j = 0; j < 4; ++j) { float o = (float)o0[j] - lam * oacc[md][nq][j]; oacc[md][nq][j] = o; ss += o * o; }
;           }
;           ss += shx(ss, 16); ss += shx(ss, 32);
;           const float r = rsqrtf(ss * (1.f / 128.f) + 1e-5f) * (1.f - 0.35550906759f);
; #pragma unroll
;           for (int md = 0; md < 8; ++md) {
;             f4 gg = *(const f4*)(p.in[41] + md * 16 + fq * 4); h4 o;
; #pragma unroll
;             for (int j = 0; j < 4; ++j) o[j] = (hf)(oacc[md][nq][j] * r * gg[j]);
;             *(h4*)(dst + md * 16) = o;
;           }
	v_add_f32_e32 v9, v15, v9
	v_fmamk_f32 v9, v9, 0x3c000000, v55
	v_mul_f32_e32 v15, 0x4b800000, v9
	v_cmp_gt_f32_e32 vcc, s83, v9
	s_nop 1
	v_cndmask_b32_e32 v9, v9, v15, vcc
	v_rsq_f32_e32 v9, v9
	s_nop 0
	v_mul_f32_e32 v15, 0x45800000, v9
	v_cndmask_b32_e32 v9, v9, v15, vcc
	v_mul_f32_e32 v132, 0x3f24fd5c, v9
	v_pk_mul_f32 v[184:185], v[184:185], v[132:133] op_sel_hi:[1,0]
	v_pk_mul_f32 v[186:187], v[186:187], v[132:133] op_sel_hi:[1,0]
	v_pk_mul_f32 v[172:173], v[172:173], v[132:133] op_sel_hi:[1,0]
	v_pk_mul_f32 v[134:135], v[134:135], v[132:133] op_sel_hi:[1,0]
	v_pk_mul_f32 v[182:183], v[182:183], v[132:133] op_sel_hi:[1,0]
	v_pk_mul_f32 v[6:7], v[6:7], v[132:133] op_sel_hi:[1,0]
	v_pk_mul_f32 v[10:11], v[10:11], v[132:133] op_sel_hi:[1,0]
	v_mov_b32_e32 v9, v211
	v_mov_b32_e32 v211, v137
	s_waitcnt vmcnt(0)
	v_pk_mul_f32 v[168:169], v[168:169], v[184:185]
	v_pk_mul_f32 v[170:171], v[170:171], v[186:187]
	v_cvt_pk_f16_f32 v168, v168, v169
	v_cvt_pk_f16_f32 v169, v170, v171
	global_store_dwordx2 v[206:207], v[168:169], off offset:2048
	global_load_dwordx4 v[168:171], v[200:201], off offset:64
	v_pk_mul_f32 v[184:185], v[188:189], v[132:133] op_sel_hi:[1,0]
	v_pk_mul_f32 v[188:189], v[204:205], v[132:133] op_sel_hi:[1,0]
	v_pk_mov_b32 v[204:205], v[12:13], v[12:13] op_sel:[1,0]
	s_waitcnt vmcnt(0)
	v_pk_mul_f32 v[168:169], v[168:169], v[172:173]
	v_pk_mul_f32 v[170:171], v[170:171], v[184:185]
	v_cvt_pk_f16_f32 v168, v168, v169
	v_cvt_pk_f16_f32 v169, v170, v171
	global_store_dwordx2 v[206:207], v[168:169], off offset:2080
	global_load_dwordx4 v[168:171], v[200:201], off offset:128
	v_pk_mul_f32 v[172:173], v[174:175], v[132:133] op_sel_hi:[1,0]
	v_pk_mul_f32 v[174:175], v[190:191], v[132:133] op_sel_hi:[1,0]
	v_mov_b32_e32 v15, v205
	v_mov_b32_e32 v205, v140
	v_pk_mov_b32 v[190:191], v[24:25], v[24:25] op_sel:[1,0]
	s_waitcnt vmcnt(0)
	v_pk_mul_f32 v[168:169], v[168:169], v[172:173]
	v_pk_mul_f32 v[170:171], v[170:171], v[174:175]
	v_cvt_pk_f16_f32 v168, v168, v169
	v_cvt_pk_f16_f32 v169, v170, v171
	global_store_dwordx2 v[206:207], v[168:169], off offset:2112
	global_load_dwordx4 v[168:171], v[200:201], off offset:192
	v_pk_mul_f32 v[172:173], v[176:177], v[132:133] op_sel_hi:[1,0]
	v_pk_mul_f32 v[174:175], v[194:195], v[132:133] op_sel_hi:[1,0]
	v_mov_b32_e32 v27, v191
	v_mov_b32_e32 v191, v159
	v_pk_mov_b32 v[194:195], v[20:21], v[20:21] op_sel:[1,0]
	s_waitcnt vmcnt(0)
	v_pk_mul_f32 v[168:169], v[168:169], v[172:173]
	v_pk_mul_f32 v[170:171], v[170:171], v[174:175]
	v_cvt_pk_f16_f32 v168, v168, v169
	v_cvt_pk_f16_f32 v169, v170, v171
	global_store_dwordx2 v[206:207], v[168:169], off offset:2144
	global_load_dwordx4 v[168:171], v[200:201], off offset:256
	v_pk_mul_f32 v[172:173], v[178:179], v[132:133] op_sel_hi:[1,0]
	v_mov_b32_e32 v23, v195
	v_mov_b32_e32 v195, v149
	s_waitcnt vmcnt(0)
	v_pk_mul_f32 v[168:169], v[168:169], v[172:173]
	v_pk_mul_f32 v[134:135], v[170:171], v[134:135]
	v_cvt_pk_f16_f32 v168, v168, v169
	v_cvt_pk_f16_f32 v169, v134, v135
	global_store_dwordx2 v[206:207], v[168:169], off offset:2176
	global_load_dwordx4 v[168:171], v[200:201], off offset:320
	v_pk_mul_f32 v[134:135], v[180:181], v[132:133] op_sel_hi:[1,0]
	v_pk_mul_f32 v[172:173], v[202:203], v[132:133] op_sel_hi:[1,0]
	v_pk_mov_b32 v[202:203], v[16:17], v[16:17] op_sel:[1,0]
	s_waitcnt vmcnt(0)
	v_pk_mul_f32 v[134:135], v[168:169], v[134:135]
	v_pk_mul_f32 v[168:169], v[170:171], v[172:173]
	v_cvt_pk_f16_f32 v134, v134, v135
	v_cvt_pk_f16_f32 v135, v168, v169
	global_store_dwordx2 v[206:207], v[134:135], off offset:2208
	global_load_dwordx4 v[168:171], v[200:201], off offset:384
	s_nop 0
	global_load_dwordx2 v[134:135], v[208:209], off offset:2272
	global_load_dwordx2 v[172:173], v[208:209], off offset:2048
	global_load_dwordx2 v[174:175], v[208:209], off offset:2080
	global_load_dwordx2 v[176:177], v[208:209], off offset:2112
	global_load_dwordx2 v[178:179], v[208:209], off offset:2144
	global_load_dwordx2 v[180:181], v[208:209], off offset:2176
	global_load_dwordx2 v[184:185], v[208:209], off offset:2208
	global_load_dwordx2 v[186:187], v[208:209], off offset:2240
	v_mov_b32_e32 v19, v203
	v_mov_b32_e32 v203, v144
	s_waitcnt vmcnt(8)
	v_pk_mul_f32 v[168:169], v[168:169], v[182:183]
	v_pk_mul_f32 v[170:171], v[170:171], v[188:189]
	v_cvt_pk_f16_f32 v168, v168, v169
	v_cvt_pk_f16_f32 v169, v170, v171
	global_store_dwordx2 v[206:207], v[168:169], off offset:2240
	global_load_dwordx4 v[168:171], v[200:201], off offset:448
	s_waitcnt vmcnt(9)
	v_cvt_f32_f16_sdwa v133, v134 dst_sel:DWORD dst_unused:UNUSED_PAD src0_sel:WORD_1
	v_cvt_f32_f16_e32 v132, v134
	v_cvt_f32_f16_sdwa v213, v135 dst_sel:DWORD dst_unused:UNUSED_PAD src0_sel:WORD_1
	v_cvt_f32_f16_e32 v212, v135
	s_waitcnt vmcnt(8)
	v_cvt_f32_f16_sdwa v135, v172 dst_sel:DWORD dst_unused:UNUSED_PAD src0_sel:WORD_1
	v_cvt_f32_f16_e32 v134, v172
	v_pk_mov_b32 v[182:183], v[46:47], v[46:47] op_sel:[1,0]
	v_cvt_f32_f16_sdwa v215, v173 dst_sel:DWORD dst_unused:UNUSED_PAD src0_sel:WORD_1
	v_mov_b32_e32 v35, v183
	v_cvt_f32_f16_e32 v214, v173
	s_waitcnt vmcnt(7)
	v_cvt_f32_f16_sdwa v173, v174 dst_sel:DWORD dst_unused:UNUSED_PAD src0_sel:WORD_1
	v_cvt_f32_f16_e32 v172, v174
	v_cvt_f32_f16_sdwa v217, v175 dst_sel:DWORD dst_unused:UNUSED_PAD src0_sel:WORD_1
	v_cvt_f32_f16_e32 v216, v175
	s_waitcnt vmcnt(6)
	v_cvt_f32_f16_sdwa v175, v176 dst_sel:DWORD dst_unused:UNUSED_PAD src0_sel:WORD_1
	v_cvt_f32_f16_e32 v174, v176
	v_cvt_f32_f16_sdwa v219, v177 dst_sel:DWORD dst_unused:UNUSED_PAD src0_sel:WORD_1
	v_cvt_f32_f16_e32 v218, v177
	s_waitcnt vmcnt(5)
; __device__ __forceinline__ void attn_phase(const Params& p, char* smem, int coff) {
;     ...
;           for (int md = 0; md < 8; ++md) {
;             h4 o0 = *(const h4*)(dst + md * 16);
; #pragma unroll
;             for (int j = 0; j < 4; ++j) { float o = (float)o0[j] - lam * oacc[md][nq][j]; oacc[md][nq][j] = o; ss += o * o; }
;           }
;           ss += shx(ss, 16); ss += shx(ss, 32);
	v_cvt_f32_f16_sdwa v177, v178 dst_sel:DWORD dst_unused:UNUSED_PAD src0_sel:WORD_1
	v_cvt_f32_f16_e32 v176, v178
	v_cvt_f32_f16_sdwa v221, v179 dst_sel:DWORD dst_unused:UNUSED_PAD src0_sel:WORD_1
	v_cvt_f32_f16_e32 v220, v179
	s_waitcnt vmcnt(4)
	v_cvt_f32_f16_sdwa v179, v180 dst_sel:DWORD dst_unused:UNUSED_PAD src0_sel:WORD_1
	v_cvt_f32_f16_e32 v178, v180
	v_cvt_f32_f16_sdwa v229, v181 dst_sel:DWORD dst_unused:UNUSED_PAD src0_sel:WORD_1
	v_cvt_f32_f16_e32 v228, v181
	s_waitcnt vmcnt(3)
	v_cvt_f32_f16_sdwa v181, v184 dst_sel:DWORD dst_unused:UNUSED_PAD src0_sel:WORD_1
	v_cvt_f32_f16_e32 v180, v184
	v_cvt_f32_f16_sdwa v231, v185 dst_sel:DWORD dst_unused:UNUSED_PAD src0_sel:WORD_1
	v_cvt_f32_f16_e32 v230, v185
	s_waitcnt vmcnt(2)
	v_cvt_f32_f16_sdwa v185, v186 dst_sel:DWORD dst_unused:UNUSED_PAD src0_sel:WORD_1
	v_cvt_f32_f16_e32 v184, v186
	v_cvt_f32_f16_sdwa v233, v187 dst_sel:DWORD dst_unused:UNUSED_PAD src0_sel:WORD_1
	v_cvt_f32_f16_e32 v232, v187
	v_pk_fma_f32 v[186:187], v[192:193], v[0:1], v[132:133] neg_lo:[1,0,0] neg_hi:[1,0,0]
	v_pk_fma_f32 v[234:235], v[192:193], v[34:35], v[134:135] neg_lo:[1,0,0] neg_hi:[1,0,0]
	v_mov_b32_e32 v183, v167
	v_pk_mov_b32 v[188:189], v[28:29], v[28:29] op_sel:[1,0]
	v_pk_fma_f32 v[182:183], v[192:193], v[182:183], v[214:215] neg_lo:[1,0,0] neg_hi:[1,0,0]
	v_mov_b32_e32 v31, v189
	v_pk_fma_f32 v[212:213], v[192:193], v[2:3], v[212:213] neg_lo:[1,0,0] neg_hi:[1,0,0]
	v_pk_fma_f32 v[172:173], v[192:193], v[30:31], v[172:173] neg_lo:[1,0,0] neg_hi:[1,0,0]
	v_mov_b32_e32 v189, v165
	v_pk_mul_f32 v[214:215], v[172:173], v[172:173]
	v_pk_fma_f32 v[188:189], v[192:193], v[188:189], v[216:217] neg_lo:[1,0,0] neg_hi:[1,0,0]
	v_pk_fma_f32 v[174:175], v[192:193], v[26:27], v[174:175] neg_lo:[1,0,0] neg_hi:[1,0,0]
	v_pk_mul_f32 v[216:217], v[188:189], v[188:189]
	v_pk_fma_f32 v[190:191], v[192:193], v[190:191], v[218:219] neg_lo:[1,0,0] neg_hi:[1,0,0]
	v_pk_mul_f32 v[218:219], v[174:175], v[174:175]
	v_pk_fma_f32 v[194:195], v[192:193], v[194:195], v[220:221] neg_lo:[1,0,0] neg_hi:[1,0,0]
	v_pk_mul_f32 v[220:221], v[190:191], v[190:191]
	v_pk_fma_f32 v[176:177], v[192:193], v[22:23], v[176:177] neg_lo:[1,0,0] neg_hi:[1,0,0]
	v_pk_fma_f32 v[178:179], v[192:193], v[18:19], v[178:179] neg_lo:[1,0,0] neg_hi:[1,0,0]
	s_waitcnt vmcnt(0)
	v_pk_mul_f32 v[6:7], v[168:169], v[6:7]
	v_pk_mul_f32 v[10:11], v[170:171], v[10:11]
	v_cvt_pk_f16_f32 v6, v6, v7
	v_cvt_pk_f16_f32 v7, v10, v11
	global_store_dwordx2 v[206:207], v[6:7], off offset:2272
	global_load_dwordx4 v[132:135], v[200:201], off
	v_pk_fma_f32 v[168:169], v[192:193], v[204:205], v[230:231] neg_lo:[1,0,0] neg_hi:[1,0,0]
	v_pk_mul_f32 v[204:205], v[234:235], v[234:235]
	v_pk_fma_f32 v[10:11], v[192:193], v[14:15], v[180:181] neg_lo:[1,0,0] neg_hi:[1,0,0]
	v_pk_fma_f32 v[180:181], v[192:193], v[210:211], v[232:233] neg_lo:[1,0,0] neg_hi:[1,0,0]
	v_pk_mul_f32 v[210:211], v[182:183], v[182:183]
	v_add_f32_e32 v3, v204, v205
	v_add_f32_e32 v3, v210, v3
	v_add_f32_e32 v3, v211, v3
	v_add_f32_e32 v3, v214, v3
	v_add_f32_e32 v3, v215, v3
	v_add_f32_e32 v3, v216, v3
	v_add_f32_e32 v3, v217, v3
	v_add_f32_e32 v3, v218, v3
	v_add_f32_e32 v3, v219, v3
	v_add_f32_e32 v3, v220, v3
	v_pk_fma_f32 v[6:7], v[192:193], v[202:203], v[228:229] neg_lo:[1,0,0] neg_hi:[1,0,0]
	v_pk_mul_f32 v[228:229], v[176:177], v[176:177]
	v_add_f32_e32 v3, v221, v3
	v_add_f32_e32 v3, v228, v3
	v_pk_mul_f32 v[230:231], v[194:195], v[194:195]
	v_add_f32_e32 v3, v229, v3
	v_add_f32_e32 v3, v230, v3
	v_pk_mul_f32 v[232:233], v[178:179], v[178:179]
	v_add_f32_e32 v3, v231, v3
	v_add_f32_e32 v3, v232, v3
	v_pk_mul_f32 v[236:237], v[6:7], v[6:7]
	v_add_f32_e32 v3, v233, v3
	v_add_f32_e32 v3, v236, v3
	v_pk_mul_f32 v[238:239], v[10:11], v[10:11]
	v_add_f32_e32 v3, v237, v3
	v_add_f32_e32 v3, v238, v3
	v_pk_mul_f32 v[240:241], v[168:169], v[168:169]
	v_add_f32_e32 v3, v239, v3
	v_pk_fma_f32 v[170:171], v[192:193], v[8:9], v[184:185] neg_lo:[1,0,0] neg_hi:[1,0,0]
	v_add_f32_e32 v3, v240, v3
	v_pk_mul_f32 v[242:243], v[170:171], v[170:171]
	v_add_f32_e32 v3, v241, v3
	v_add_f32_e32 v3, v242, v3
	v_pk_mul_f32 v[244:245], v[180:181], v[180:181]
	v_add_f32_e32 v3, v243, v3
	v_add_f32_e32 v3, v244, v3
	v_pk_mul_f32 v[184:185], v[186:187], v[186:187]
	v_add_f32_e32 v3, v245, v3
	v_add_f32_e32 v3, v184, v3
	v_pk_mul_f32 v[202:203], v[212:213], v[212:213]
	v_add_f32_e32 v3, v185, v3
	v_add_f32_e32 v3, v202, v3
	v_add_f32_e32 v3, v203, v3
	ds_swizzle_b32 v9, v3 offset:swizzle(SWAP,16)
	s_waitcnt lgkmcnt(0)
; __device__ __forceinline__ void attn_phase(const Params& p, char* smem, int coff) {
;     ...
;           ss += shx(ss, 16); ss += shx(ss, 32);
;           const float r = rsqrtf(ss * (1.f / 128.f) + 1e-5f) * (1.f - 0.35550906759f);
; #pragma unroll
;           for (int md = 0; md < 8; ++md) {
;             f4 gg = *(const f4*)(p.in[41] + md * 16 + fq * 4); h4 o;
; #pragma unroll
;             for (int j = 0; j < 4; ++j) o[j] = (hf)(oacc[md][nq][j] * r * gg[j]);
;             *(h4*)(dst + md * 16) = o;
;           }
	v_add_f32_e32 v3, v3, v9
	v_lshlrev_b32_e32 v9, 2, v33
	v_bitop3_b32 v9, v9, s3, v226 bitop3:0x6c
	ds_bpermute_b32 v9, v9, v3
	s_waitcnt lgkmcnt(0)
	v_add_f32_e32 v3, v3, v9
	v_fmamk_f32 v3, v3, 0x3c000000, v55
	v_mul_f32_e32 v9, 0x4b800000, v3
	v_cmp_gt_f32_e32 vcc, s83, v3
	s_nop 1
	v_cndmask_b32_e32 v3, v3, v9, vcc
	v_rsq_f32_e32 v3, v3
	s_nop 0
	v_mul_f32_e32 v9, 0x45800000, v3
	v_cndmask_b32_e32 v3, v3, v9, vcc
	v_mul_f32_e32 v136, 0x3f24fd5c, v3
	v_pk_mul_f32 v[184:185], v[234:235], v[136:137] op_sel_hi:[1,0]
	v_pk_mul_f32 v[182:183], v[182:183], v[136:137] op_sel_hi:[1,0]
	v_pk_mul_f32 v[172:173], v[172:173], v[136:137] op_sel_hi:[1,0]
	v_pk_mul_f32 v[6:7], v[6:7], v[136:137] op_sel_hi:[1,0]
	s_waitcnt vmcnt(0)
	v_pk_mul_f32 v[132:133], v[132:133], v[184:185]
	v_pk_mul_f32 v[134:135], v[134:135], v[182:183]
	v_cvt_pk_f16_f32 v132, v132, v133
	v_cvt_pk_f16_f32 v133, v134, v135
	global_store_dwordx2 v[208:209], v[132:133], off offset:2048
	global_load_dwordx4 v[132:135], v[200:201], off offset:64
	v_pk_mul_f32 v[182:183], v[188:189], v[136:137] op_sel_hi:[1,0]
	v_mul_f32_e32 v3, v212, v136
	v_mul_f32_e32 v9, v213, v136
	s_waitcnt vmcnt(0)
	v_pk_mul_f32 v[132:133], v[132:133], v[172:173]
	v_pk_mul_f32 v[134:135], v[134:135], v[182:183]
	v_cvt_pk_f16_f32 v132, v132, v133
	v_cvt_pk_f16_f32 v133, v134, v135
	global_store_dwordx2 v[208:209], v[132:133], off offset:2080
	global_load_dwordx4 v[132:135], v[200:201], off offset:128
	v_pk_mul_f32 v[172:173], v[174:175], v[136:137] op_sel_hi:[1,0]
	v_pk_mul_f32 v[174:175], v[190:191], v[136:137] op_sel_hi:[1,0]
	s_waitcnt vmcnt(0)
	v_pk_mul_f32 v[132:133], v[132:133], v[172:173]
	v_pk_mul_f32 v[134:135], v[134:135], v[174:175]
	v_cvt_pk_f16_f32 v132, v132, v133
	v_cvt_pk_f16_f32 v133, v134, v135
	global_store_dwordx2 v[208:209], v[132:133], off offset:2112
	global_load_dwordx4 v[132:135], v[200:201], off offset:192
	v_pk_mul_f32 v[172:173], v[176:177], v[136:137] op_sel_hi:[1,0]
	v_pk_mul_f32 v[174:175], v[194:195], v[136:137] op_sel_hi:[1,0]
	s_waitcnt vmcnt(0)
	v_pk_mul_f32 v[132:133], v[132:133], v[172:173]
	v_pk_mul_f32 v[134:135], v[134:135], v[174:175]
	v_cvt_pk_f16_f32 v132, v132, v133
	v_cvt_pk_f16_f32 v133, v134, v135
	global_store_dwordx2 v[208:209], v[132:133], off offset:2144
	global_load_dwordx4 v[132:135], v[200:201], off offset:256
	v_pk_mul_f32 v[172:173], v[178:179], v[136:137] op_sel_hi:[1,0]
	s_waitcnt vmcnt(0)
	v_pk_mul_f32 v[6:7], v[134:135], v[6:7]
	v_pk_mul_f32 v[132:133], v[132:133], v[172:173]
	s_nop 0
	v_cvt_pk_f16_f32 v132, v132, v133
	v_cvt_pk_f16_f32 v133, v6, v7
	global_store_dwordx2 v[208:209], v[132:133], off offset:2176
	global_load_dwordx4 v[132:135], v[200:201], off offset:320
	v_pk_mul_f32 v[6:7], v[10:11], v[136:137] op_sel_hi:[1,0]
	v_pk_mul_f32 v[10:11], v[168:169], v[136:137] op_sel_hi:[1,0]
	s_waitcnt vmcnt(0)
	v_pk_mul_f32 v[6:7], v[132:133], v[6:7]
	v_pk_mul_f32 v[10:11], v[134:135], v[10:11]
	v_cvt_pk_f16_f32 v6, v6, v7
	v_cvt_pk_f16_f32 v7, v10, v11
	global_store_dwordx2 v[208:209], v[6:7], off offset:2208
	global_load_dwordx4 v[132:135], v[200:201], off offset:384
	v_pk_mul_f32 v[6:7], v[170:171], v[136:137] op_sel_hi:[1,0]
	v_pk_mul_f32 v[10:11], v[180:181], v[136:137] op_sel_hi:[1,0]
	s_waitcnt vmcnt(0)
	v_pk_mul_f32 v[6:7], v[132:133], v[6:7]
	v_pk_mul_f32 v[10:11], v[134:135], v[10:11]
	v_cvt_pk_f16_f32 v6, v6, v7
	v_cvt_pk_f16_f32 v7, v10, v11
	global_store_dwordx2 v[208:209], v[6:7], off offset:2240
	global_load_dwordx4 v[132:135], v[200:201], off offset:448
	v_pk_mul_f32 v[6:7], v[186:187], v[136:137] op_sel_hi:[1,0]
	s_waitcnt vmcnt(0)
	v_fma_mixlo_f16 v10, v134, v3, 0
	v_pk_mul_f32 v[6:7], v[132:133], v[6:7]
	v_mul_f32_e32 v3, v135, v9
	v_cvt_pk_f16_f32 v6, v6, v7
	v_pack_b32_f16 v7, v10, 0
	s_cbranch_execnz .LBB0_1946
	s_branch .LBB0_1945
